# K loops: s_setprio 0 moved from before to after the post-MMA barrier (off the MFMA half's critical path)
# speedup vs baseline: 1.0092x; 1.0092x over previous
.LBB0_79:
	s_add_u32 s30, s28, 0xfffc0080
	s_addc_u32 s31, s29, -1
	s_add_i32 s63, 0, 0x10000
	s_cmp_eq_u32 s62, 12
	s_cselect_b32 s35, s5, s31
	s_cselect_b32 s34, s21, s30
	v_add_u32_e32 v146, s63, v148
	s_cselect_b32 s31, s19, s61
	s_cselect_b32 s30, s27, s60
	s_add_i32 s66, 0, 0x14000
	ds_read_b128 v[142:145], v146
	ds_read_b128 v[152:155], v146 offset:1024
	ds_read_b128 v[156:159], v146 offset:2048
	ds_read_b128 v[160:163], v146 offset:3072
	v_add_u32_e32 v146, s66, v148
	ds_read_b128 v[164:167], v146
	ds_read_b128 v[168:171], v146 offset:1024
	ds_read_b128 v[172:175], v146 offset:2048
	ds_read_b128 v[176:179], v146 offset:3072
	v_lshl_add_u64 v[146:147], s[28:29], 0, v[138:139]
	s_add_i32 m0, s38, 0xc000
	ds_read_b128 v[180:183], v150
	ds_read_b128 v[184:187], v150 offset:1024
	ds_read_b128 v[188:191], v150 offset:2048
	ds_read_b128 v[192:195], v150 offset:3072
	ds_read_b128 v[196:199], v150 offset:4096
	ds_read_b128 v[200:203], v150 offset:5120
	ds_read_b128 v[204:207], v150 offset:6144
	ds_read_b128 v[208:211], v150 offset:7168
	global_load_lds_dwordx4 v[146:147], off
	v_lshl_add_u64 v[146:147], s[28:29], 0, v[140:141]
	s_add_i32 m0, s38, 0xe000
	s_nop 0
	global_load_lds_dwordx4 v[146:147], off
	s_waitcnt vmcnt(8)
	s_waitcnt lgkmcnt(0)
	s_barrier
	s_setprio 1
	s_waitcnt lgkmcnt(0)
	v_mfma_f32_16x16x32_bf16 v[130:133], v[142:145], v[180:183], v[130:133]
	v_mfma_f32_16x16x32_bf16 v[126:129], v[156:159], v[180:183], v[126:129]
	v_mfma_f32_16x16x32_bf16 v[114:117], v[142:145], v[188:191], v[114:117]
	v_mfma_f32_16x16x32_bf16 v[110:113], v[156:159], v[188:191], v[110:113]
	v_mfma_f32_16x16x32_bf16 v[98:101], v[142:145], v[196:199], v[98:101]
	v_mfma_f32_16x16x32_bf16 v[94:97], v[156:159], v[196:199], v[94:97]
	v_mfma_f32_16x16x32_bf16 v[82:85], v[142:145], v[204:207], v[82:85]
	v_mfma_f32_16x16x32_bf16 v[78:81], v[156:159], v[204:207], v[78:81]
	v_mfma_f32_16x16x32_bf16 v[130:133], v[152:155], v[184:187], v[130:133]
	v_mfma_f32_16x16x32_bf16 v[126:129], v[160:163], v[184:187], v[126:129]
	v_mfma_f32_16x16x32_bf16 v[114:117], v[152:155], v[192:195], v[114:117]
	v_mfma_f32_16x16x32_bf16 v[110:113], v[160:163], v[192:195], v[110:113]
	v_mfma_f32_16x16x32_bf16 v[98:101], v[152:155], v[200:203], v[98:101]
	v_mfma_f32_16x16x32_bf16 v[94:97], v[160:163], v[200:203], v[94:97]
	v_mfma_f32_16x16x32_bf16 v[82:85], v[152:155], v[208:211], v[82:85]
	v_mfma_f32_16x16x32_bf16 v[78:81], v[160:163], v[208:211], v[78:81]
	s_setprio 0
	s_setprio 1
	v_mfma_f32_16x16x32_bf16 v[122:125], v[164:167], v[180:183], v[122:125]
	v_mfma_f32_16x16x32_bf16 v[118:121], v[172:175], v[180:183], v[118:121]
	v_mfma_f32_16x16x32_bf16 v[106:109], v[164:167], v[188:191], v[106:109]
	v_mfma_f32_16x16x32_bf16 v[102:105], v[172:175], v[188:191], v[102:105]
	v_mfma_f32_16x16x32_bf16 v[90:93], v[164:167], v[196:199], v[90:93]
	v_mfma_f32_16x16x32_bf16 v[86:89], v[172:175], v[196:199], v[86:89]
	v_mfma_f32_16x16x32_bf16 v[74:77], v[164:167], v[204:207], v[74:77]
	v_mfma_f32_16x16x32_bf16 v[70:73], v[172:175], v[204:207], v[70:73]
	v_mfma_f32_16x16x32_bf16 v[122:125], v[168:171], v[184:187], v[122:125]
	v_mfma_f32_16x16x32_bf16 v[118:121], v[176:179], v[184:187], v[118:121]
	v_mfma_f32_16x16x32_bf16 v[106:109], v[168:171], v[192:195], v[106:109]
	v_mfma_f32_16x16x32_bf16 v[102:105], v[176:179], v[192:195], v[102:105]
	v_mfma_f32_16x16x32_bf16 v[90:93], v[168:171], v[200:203], v[90:93]
	v_mfma_f32_16x16x32_bf16 v[86:89], v[176:179], v[200:203], v[86:89]
	v_mfma_f32_16x16x32_bf16 v[74:77], v[168:171], v[208:211], v[74:77]
	v_mfma_f32_16x16x32_bf16 v[70:73], v[176:179], v[208:211], v[70:73]
	s_barrier
	s_setprio 0
	s_add_i32 s63, s63, s37
	v_lshl_add_u64 v[146:147], s[30:31], 0, v[0:1]
	s_mov_b32 m0, s63
	ds_read_b128 v[180:183], v150 offset:16384
	ds_read_b128 v[184:187], v150 offset:17408
	ds_read_b128 v[188:191], v150 offset:18432
	ds_read_b128 v[192:195], v150 offset:19456
	ds_read_b128 v[196:199], v150 offset:20480
	ds_read_b128 v[200:203], v150 offset:21504
	ds_read_b128 v[204:207], v150 offset:22528
	ds_read_b128 v[208:211], v150 offset:23552
	global_load_lds_dwordx4 v[146:147], off
	s_add_i32 m0, s63, 0x2000
	s_add_u32 s64, s30, 0x580000
	v_lshl_add_u64 v[212:213], s[30:31], 0, v[136:137]
	s_addc_u32 s65, s31, 0
	s_add_i32 s63, s66, s37
	global_load_lds_dwordx4 v[212:213], off
	v_lshl_add_u64 v[214:215], s[64:65], 0, v[0:1]
	s_mov_b32 m0, s63
	v_lshl_add_u64 v[216:217], s[34:35], 0, v[134:135]
	global_load_lds_dwordx4 v[214:215], off
	v_lshl_add_u64 v[214:215], s[64:65], 0, v[136:137]
	s_add_i32 m0, s63, 0x2000
	s_nop 0
	global_load_lds_dwordx4 v[214:215], off
	v_lshl_add_u64 v[214:215], s[34:35], 0, v[2:3]
	s_mov_b32 m0, s38
	s_nop 0
	global_load_lds_dwordx4 v[214:215], off
	s_mov_b32 m0, s39
	s_nop 0
	global_load_lds_dwordx4 v[216:217], off
	s_waitcnt vmcnt(8)
	s_waitcnt lgkmcnt(0)
	s_barrier
	s_setprio 1
	s_waitcnt lgkmcnt(0)
	v_mfma_f32_16x16x32_bf16 v[66:69], v[142:145], v[180:183], v[66:69]
	v_mfma_f32_16x16x32_bf16 v[62:65], v[156:159], v[180:183], v[62:65]
	v_mfma_f32_16x16x32_bf16 v[50:53], v[142:145], v[188:191], v[50:53]
	v_mfma_f32_16x16x32_bf16 v[46:49], v[156:159], v[188:191], v[46:49]
	v_mfma_f32_16x16x32_bf16 v[34:37], v[142:145], v[196:199], v[34:37]
	v_mfma_f32_16x16x32_bf16 v[30:33], v[156:159], v[196:199], v[30:33]
	v_mfma_f32_16x16x32_bf16 v[18:21], v[142:145], v[204:207], v[18:21]
	v_mfma_f32_16x16x32_bf16 v[14:17], v[156:159], v[204:207], v[14:17]
	v_mfma_f32_16x16x32_bf16 v[66:69], v[152:155], v[184:187], v[66:69]
	v_mfma_f32_16x16x32_bf16 v[62:65], v[160:163], v[184:187], v[62:65]
	v_mfma_f32_16x16x32_bf16 v[50:53], v[152:155], v[192:195], v[50:53]
	v_mfma_f32_16x16x32_bf16 v[46:49], v[160:163], v[192:195], v[46:49]
	v_mfma_f32_16x16x32_bf16 v[34:37], v[152:155], v[200:203], v[34:37]
	v_mfma_f32_16x16x32_bf16 v[30:33], v[160:163], v[200:203], v[30:33]
	v_mfma_f32_16x16x32_bf16 v[18:21], v[152:155], v[208:211], v[18:21]
	v_mfma_f32_16x16x32_bf16 v[14:17], v[160:163], v[208:211], v[14:17]
	s_setprio 0
	s_setprio 1
	v_mfma_f32_16x16x32_bf16 v[58:61], v[164:167], v[180:183], v[58:61]
	v_mfma_f32_16x16x32_bf16 v[54:57], v[172:175], v[180:183], v[54:57]
	v_mfma_f32_16x16x32_bf16 v[42:45], v[164:167], v[188:191], v[42:45]
	v_mfma_f32_16x16x32_bf16 v[38:41], v[172:175], v[188:191], v[38:41]
	v_mfma_f32_16x16x32_bf16 v[26:29], v[164:167], v[196:199], v[26:29]
	v_mfma_f32_16x16x32_bf16 v[22:25], v[172:175], v[196:199], v[22:25]
	v_mfma_f32_16x16x32_bf16 v[10:13], v[164:167], v[204:207], v[10:13]
	v_mfma_f32_16x16x32_bf16 v[6:9], v[172:175], v[204:207], v[6:9]
	v_mfma_f32_16x16x32_bf16 v[58:61], v[168:171], v[184:187], v[58:61]
	v_mfma_f32_16x16x32_bf16 v[54:57], v[176:179], v[184:187], v[54:57]
	v_mfma_f32_16x16x32_bf16 v[42:45], v[168:171], v[192:195], v[42:45]
	v_mfma_f32_16x16x32_bf16 v[38:41], v[176:179], v[192:195], v[38:41]
	v_mfma_f32_16x16x32_bf16 v[26:29], v[168:171], v[200:203], v[26:29]
	v_mfma_f32_16x16x32_bf16 v[22:25], v[176:179], v[200:203], v[22:25]
	v_mfma_f32_16x16x32_bf16 v[10:13], v[168:171], v[208:211], v[10:13]
	v_mfma_f32_16x16x32_bf16 v[6:9], v[176:179], v[208:211], v[6:9]
	s_barrier
	s_setprio 0
	s_add_i32 s63, 0, 0x18000
	v_add_u32_e32 v151, s63, v148
	s_add_i32 s64, 0, 0x1c000
	ds_read_b128 v[142:145], v151
	ds_read_b128 v[152:155], v151 offset:1024
	ds_read_b128 v[156:159], v151 offset:2048
	ds_read_b128 v[160:163], v151 offset:3072
	v_add_u32_e32 v151, s64, v148
	ds_read_b128 v[164:167], v151
	ds_read_b128 v[168:171], v151 offset:1024
	ds_read_b128 v[172:175], v151 offset:2048
	ds_read_b128 v[176:179], v151 offset:3072
	s_add_u32 s34, s34, 0x40000
	s_addc_u32 s35, s35, 0
	s_mov_b32 m0, s41
	v_lshl_add_u64 v[220:221], s[34:35], 0, v[2:3]
	ds_read_b128 v[180:183], v150 offset:32768
	ds_read_b128 v[184:187], v150 offset:33792
	ds_read_b128 v[188:191], v150 offset:34816
	ds_read_b128 v[192:195], v150 offset:35840
	ds_read_b128 v[196:199], v150 offset:36864
	ds_read_b128 v[200:203], v150 offset:37888
	ds_read_b128 v[204:207], v150 offset:38912
	ds_read_b128 v[208:211], v150 offset:39936
	global_load_lds_dwordx4 v[220:221], off
	v_lshl_add_u64 v[220:221], s[34:35], 0, v[134:135]
	s_mov_b32 m0, s42
	s_nop 0
	global_load_lds_dwordx4 v[220:221], off
	s_waitcnt vmcnt(8)
	s_waitcnt lgkmcnt(0)
	s_barrier
	s_setprio 1
	s_waitcnt lgkmcnt(0)
	v_mfma_f32_16x16x32_bf16 v[130:133], v[142:145], v[180:183], v[130:133]
	v_mfma_f32_16x16x32_bf16 v[126:129], v[156:159], v[180:183], v[126:129]
	v_mfma_f32_16x16x32_bf16 v[114:117], v[142:145], v[188:191], v[114:117]
	v_mfma_f32_16x16x32_bf16 v[110:113], v[156:159], v[188:191], v[110:113]
	v_mfma_f32_16x16x32_bf16 v[98:101], v[142:145], v[196:199], v[98:101]
	v_mfma_f32_16x16x32_bf16 v[94:97], v[156:159], v[196:199], v[94:97]
	v_mfma_f32_16x16x32_bf16 v[82:85], v[142:145], v[204:207], v[82:85]
	v_mfma_f32_16x16x32_bf16 v[78:81], v[156:159], v[204:207], v[78:81]
	v_mfma_f32_16x16x32_bf16 v[130:133], v[152:155], v[184:187], v[130:133]
	v_mfma_f32_16x16x32_bf16 v[126:129], v[160:163], v[184:187], v[126:129]
	v_mfma_f32_16x16x32_bf16 v[114:117], v[152:155], v[192:195], v[114:117]
	v_mfma_f32_16x16x32_bf16 v[110:113], v[160:163], v[192:195], v[110:113]
	v_mfma_f32_16x16x32_bf16 v[98:101], v[152:155], v[200:203], v[98:101]
	v_mfma_f32_16x16x32_bf16 v[94:97], v[160:163], v[200:203], v[94:97]
	v_mfma_f32_16x16x32_bf16 v[82:85], v[152:155], v[208:211], v[82:85]
	v_mfma_f32_16x16x32_bf16 v[78:81], v[160:163], v[208:211], v[78:81]
	s_setprio 0
	s_setprio 1
	v_mfma_f32_16x16x32_bf16 v[122:125], v[164:167], v[180:183], v[122:125]
	v_mfma_f32_16x16x32_bf16 v[118:121], v[172:175], v[180:183], v[118:121]
	v_mfma_f32_16x16x32_bf16 v[106:109], v[164:167], v[188:191], v[106:109]
	v_mfma_f32_16x16x32_bf16 v[102:105], v[172:175], v[188:191], v[102:105]
	v_mfma_f32_16x16x32_bf16 v[90:93], v[164:167], v[196:199], v[90:93]
	v_mfma_f32_16x16x32_bf16 v[86:89], v[172:175], v[196:199], v[86:89]
	v_mfma_f32_16x16x32_bf16 v[74:77], v[164:167], v[204:207], v[74:77]
	v_mfma_f32_16x16x32_bf16 v[70:73], v[172:175], v[204:207], v[70:73]
	v_mfma_f32_16x16x32_bf16 v[122:125], v[168:171], v[184:187], v[122:125]
	v_mfma_f32_16x16x32_bf16 v[118:121], v[176:179], v[184:187], v[118:121]
	v_mfma_f32_16x16x32_bf16 v[106:109], v[168:171], v[192:195], v[106:109]
	v_mfma_f32_16x16x32_bf16 v[102:105], v[176:179], v[192:195], v[102:105]
	v_mfma_f32_16x16x32_bf16 v[90:93], v[168:171], v[200:203], v[90:93]
	v_mfma_f32_16x16x32_bf16 v[86:89], v[176:179], v[200:203], v[86:89]
	v_mfma_f32_16x16x32_bf16 v[74:77], v[168:171], v[208:211], v[74:77]
	v_mfma_f32_16x16x32_bf16 v[70:73], v[176:179], v[208:211], v[70:73]
	s_barrier
	s_setprio 0
	s_add_i32 s34, s63, s37
	v_lshl_add_u64 v[146:147], v[146:147], 0, s[50:51]
	s_mov_b32 m0, s34
	ds_read_b128 v[180:183], v150 offset:49152
	ds_read_b128 v[184:187], v150 offset:50176
	ds_read_b128 v[188:191], v150 offset:51200
	ds_read_b128 v[192:195], v150 offset:52224
	ds_read_b128 v[196:199], v150 offset:53248
	ds_read_b128 v[200:203], v150 offset:54272
	ds_read_b128 v[204:207], v150 offset:55296
	ds_read_b128 v[208:211], v150 offset:56320
	global_load_lds_dwordx4 v[146:147], off
	s_add_i32 m0, s34, 0x2000
	s_add_u32 s30, s30, 0x580080
	v_lshl_add_u64 v[146:147], v[212:213], 0, s[50:51]
	s_addc_u32 s31, s31, 0
	s_add_i32 s34, s64, s37
	global_load_lds_dwordx4 v[146:147], off
	v_lshl_add_u64 v[146:147], s[30:31], 0, v[0:1]
	s_mov_b32 m0, s34
	s_nop 0
	global_load_lds_dwordx4 v[146:147], off
	v_lshl_add_u64 v[146:147], s[30:31], 0, v[136:137]
	s_add_i32 m0, s34, 0x2000
	s_nop 0
	global_load_lds_dwordx4 v[146:147], off
	v_lshl_add_u64 v[146:147], v[214:215], 0, s[50:51]
	s_mov_b32 m0, s44
	s_nop 0
	global_load_lds_dwordx4 v[146:147], off
	v_lshl_add_u64 v[146:147], v[216:217], 0, s[50:51]
	s_mov_b32 m0, s45
	s_nop 0
	global_load_lds_dwordx4 v[146:147], off
	s_waitcnt vmcnt(8)
	s_waitcnt lgkmcnt(0)
	s_barrier
	s_setprio 1
	s_waitcnt lgkmcnt(0)
	v_mfma_f32_16x16x32_bf16 v[66:69], v[142:145], v[180:183], v[66:69]
	v_mfma_f32_16x16x32_bf16 v[62:65], v[156:159], v[180:183], v[62:65]
	v_mfma_f32_16x16x32_bf16 v[50:53], v[142:145], v[188:191], v[50:53]
	v_mfma_f32_16x16x32_bf16 v[46:49], v[156:159], v[188:191], v[46:49]
	v_mfma_f32_16x16x32_bf16 v[34:37], v[142:145], v[196:199], v[34:37]
	v_mfma_f32_16x16x32_bf16 v[30:33], v[156:159], v[196:199], v[30:33]
	v_mfma_f32_16x16x32_bf16 v[18:21], v[142:145], v[204:207], v[18:21]
	v_mfma_f32_16x16x32_bf16 v[14:17], v[156:159], v[204:207], v[14:17]
	v_mfma_f32_16x16x32_bf16 v[66:69], v[152:155], v[184:187], v[66:69]
	v_mfma_f32_16x16x32_bf16 v[62:65], v[160:163], v[184:187], v[62:65]
	v_mfma_f32_16x16x32_bf16 v[50:53], v[152:155], v[192:195], v[50:53]
	v_mfma_f32_16x16x32_bf16 v[46:49], v[160:163], v[192:195], v[46:49]
	v_mfma_f32_16x16x32_bf16 v[34:37], v[152:155], v[200:203], v[34:37]
	v_mfma_f32_16x16x32_bf16 v[30:33], v[160:163], v[200:203], v[30:33]
	v_mfma_f32_16x16x32_bf16 v[18:21], v[152:155], v[208:211], v[18:21]
	v_mfma_f32_16x16x32_bf16 v[14:17], v[160:163], v[208:211], v[14:17]
	s_setprio 0
	s_setprio 1
	v_mfma_f32_16x16x32_bf16 v[58:61], v[164:167], v[180:183], v[58:61]
	v_mfma_f32_16x16x32_bf16 v[54:57], v[172:175], v[180:183], v[54:57]
	v_mfma_f32_16x16x32_bf16 v[42:45], v[164:167], v[188:191], v[42:45]
	v_mfma_f32_16x16x32_bf16 v[38:41], v[172:175], v[188:191], v[38:41]
	v_mfma_f32_16x16x32_bf16 v[26:29], v[164:167], v[196:199], v[26:29]
	v_mfma_f32_16x16x32_bf16 v[22:25], v[172:175], v[196:199], v[22:25]
	v_mfma_f32_16x16x32_bf16 v[10:13], v[164:167], v[204:207], v[10:13]
	v_mfma_f32_16x16x32_bf16 v[6:9], v[172:175], v[204:207], v[6:9]
	v_mfma_f32_16x16x32_bf16 v[58:61], v[168:171], v[184:187], v[58:61]
	v_mfma_f32_16x16x32_bf16 v[54:57], v[176:179], v[184:187], v[54:57]
	v_mfma_f32_16x16x32_bf16 v[42:45], v[168:171], v[192:195], v[42:45]
	v_mfma_f32_16x16x32_bf16 v[38:41], v[176:179], v[192:195], v[38:41]
	v_mfma_f32_16x16x32_bf16 v[26:29], v[168:171], v[200:203], v[26:29]
	v_mfma_f32_16x16x32_bf16 v[22:25], v[176:179], v[200:203], v[22:25]
	v_mfma_f32_16x16x32_bf16 v[10:13], v[168:171], v[208:211], v[10:13]
	v_mfma_f32_16x16x32_bf16 v[6:9], v[176:179], v[208:211], v[6:9]
	s_barrier
	s_setprio 0
	s_add_i32 s62, s62, 2
	s_add_u32 s28, s28, 0x100
	s_addc_u32 s29, s29, 0
	s_add_u32 s60, s60, 0x100
	s_addc_u32 s61, s61, 0
	s_cmp_gt_u32 s62, 13
	s_cbranch_scc0 .LBB0_79
	s_and_b64 vcc, exec, s[16:17]
	s_cbranch_vccz .LBB0_82
	s_barrier

.LBB0_205:
	s_add_u32 s28, s26, 0xfffc0080
	s_addc_u32 s29, s27, -1
	s_add_i32 s60, 0, 0x10000
	s_cmp_eq_u32 s59, 12
	s_cselect_b32 s31, s7, s29
	s_cselect_b32 s30, s19, s28
	v_add_u32_e32 v0, s60, v164
	s_cselect_b32 s29, s17, s58
	s_cselect_b32 s28, s25, s48
	s_add_i32 s62, 0, 0x14000
	ds_read_b128 v[46:49], v0
	ds_read_b128 v[50:53], v0 offset:1024
	ds_read_b128 v[54:57], v0 offset:2048
	ds_read_b128 v[58:61], v0 offset:3072
	v_add_u32_e32 v0, s62, v164
	ds_read_b128 v[160:163], v0
	ds_read_b128 v[168:171], v0 offset:1024
	ds_read_b128 v[172:175], v0 offset:2048
	ds_read_b128 v[176:179], v0 offset:3072
	v_lshl_add_u64 v[212:213], s[26:27], 0, v[156:157]
	s_add_i32 m0, s36, 0xc000
	ds_read_b128 v[180:183], v166
	ds_read_b128 v[184:187], v166 offset:1024
	ds_read_b128 v[188:191], v166 offset:2048
	ds_read_b128 v[192:195], v166 offset:3072
	ds_read_b128 v[196:199], v166 offset:4096
	ds_read_b128 v[200:203], v166 offset:5120
	ds_read_b128 v[204:207], v166 offset:6144
	ds_read_b128 v[208:211], v166 offset:7168
	global_load_lds_dwordx4 v[212:213], off
	v_lshl_add_u64 v[212:213], s[26:27], 0, v[158:159]
	s_add_i32 m0, s36, 0xe000
	s_nop 0
	global_load_lds_dwordx4 v[212:213], off
	s_waitcnt vmcnt(8)
	s_waitcnt lgkmcnt(0)
	s_barrier
	s_setprio 1
	s_waitcnt lgkmcnt(0)
	v_mfma_f32_16x16x32_bf16 v[146:149], v[46:49], v[180:183], v[146:149]
	v_mfma_f32_16x16x32_bf16 v[142:145], v[54:57], v[180:183], v[142:145]
	v_mfma_f32_16x16x32_bf16 v[130:133], v[46:49], v[188:191], v[130:133]
	v_mfma_f32_16x16x32_bf16 v[126:129], v[54:57], v[188:191], v[126:129]
	v_mfma_f32_16x16x32_bf16 v[114:117], v[46:49], v[196:199], v[114:117]
	v_mfma_f32_16x16x32_bf16 v[110:113], v[54:57], v[196:199], v[110:113]
	v_mfma_f32_16x16x32_bf16 v[98:101], v[46:49], v[204:207], v[98:101]
	v_mfma_f32_16x16x32_bf16 v[94:97], v[54:57], v[204:207], v[94:97]
	v_mfma_f32_16x16x32_bf16 v[146:149], v[50:53], v[184:187], v[146:149]
	v_mfma_f32_16x16x32_bf16 v[142:145], v[58:61], v[184:187], v[142:145]
	v_mfma_f32_16x16x32_bf16 v[130:133], v[50:53], v[192:195], v[130:133]
	v_mfma_f32_16x16x32_bf16 v[126:129], v[58:61], v[192:195], v[126:129]
	v_mfma_f32_16x16x32_bf16 v[114:117], v[50:53], v[200:203], v[114:117]
	v_mfma_f32_16x16x32_bf16 v[110:113], v[58:61], v[200:203], v[110:113]
	v_mfma_f32_16x16x32_bf16 v[98:101], v[50:53], v[208:211], v[98:101]
	v_mfma_f32_16x16x32_bf16 v[94:97], v[58:61], v[208:211], v[94:97]
	s_setprio 0
	s_setprio 1
	v_mfma_f32_16x16x32_bf16 v[138:141], v[160:163], v[180:183], v[138:141]
	v_mfma_f32_16x16x32_bf16 v[134:137], v[172:175], v[180:183], v[134:137]
	v_mfma_f32_16x16x32_bf16 v[122:125], v[160:163], v[188:191], v[122:125]
	v_mfma_f32_16x16x32_bf16 v[118:121], v[172:175], v[188:191], v[118:121]
	v_mfma_f32_16x16x32_bf16 v[106:109], v[160:163], v[196:199], v[106:109]
	v_mfma_f32_16x16x32_bf16 v[102:105], v[172:175], v[196:199], v[102:105]
	v_mfma_f32_16x16x32_bf16 v[90:93], v[160:163], v[204:207], v[90:93]
	v_mfma_f32_16x16x32_bf16 v[86:89], v[172:175], v[204:207], v[86:89]
	v_mfma_f32_16x16x32_bf16 v[138:141], v[168:171], v[184:187], v[138:141]
	v_mfma_f32_16x16x32_bf16 v[134:137], v[176:179], v[184:187], v[134:137]
	v_mfma_f32_16x16x32_bf16 v[122:125], v[168:171], v[192:195], v[122:125]
	v_mfma_f32_16x16x32_bf16 v[118:121], v[176:179], v[192:195], v[118:121]
	v_mfma_f32_16x16x32_bf16 v[106:109], v[168:171], v[200:203], v[106:109]
	v_mfma_f32_16x16x32_bf16 v[102:105], v[176:179], v[200:203], v[102:105]
	v_mfma_f32_16x16x32_bf16 v[90:93], v[168:171], v[208:211], v[90:93]
	v_mfma_f32_16x16x32_bf16 v[86:89], v[176:179], v[208:211], v[86:89]
	s_barrier
	s_setprio 0
	s_add_i32 s60, s60, s35
	v_lshl_add_u64 v[212:213], s[28:29], 0, v[150:151]
	s_mov_b32 m0, s60
	ds_read_b128 v[180:183], v166 offset:16384
	ds_read_b128 v[184:187], v166 offset:17408
	ds_read_b128 v[188:191], v166 offset:18432
	ds_read_b128 v[192:195], v166 offset:19456
	ds_read_b128 v[196:199], v166 offset:20480
	ds_read_b128 v[200:203], v166 offset:21504
	ds_read_b128 v[204:207], v166 offset:22528
	ds_read_b128 v[208:211], v166 offset:23552
	global_load_lds_dwordx4 v[212:213], off
	s_add_i32 m0, s60, 0x2000
	s_add_u32 s60, s28, 0x40000
	v_lshl_add_u64 v[214:215], s[28:29], 0, v[154:155]
	s_addc_u32 s61, s29, 0
	s_add_i32 s62, s62, s35
	global_load_lds_dwordx4 v[214:215], off
	v_lshl_add_u64 v[216:217], s[60:61], 0, v[150:151]
	s_mov_b32 m0, s62
	v_lshl_add_u64 v[220:221], s[30:31], 0, v[152:153]
	global_load_lds_dwordx4 v[216:217], off
	v_lshl_add_u64 v[216:217], s[60:61], 0, v[154:155]
	s_add_i32 m0, s62, 0x2000
	s_nop 0
	global_load_lds_dwordx4 v[216:217], off
	v_lshl_add_u64 v[216:217], s[30:31], 0, v[2:3]
	s_mov_b32 m0, s36
	s_nop 0
	global_load_lds_dwordx4 v[216:217], off
	s_mov_b32 m0, s37
	s_nop 0
	global_load_lds_dwordx4 v[220:221], off
	s_waitcnt vmcnt(8)
	s_waitcnt lgkmcnt(0)
	s_barrier
	s_setprio 1
	s_waitcnt lgkmcnt(0)
	v_mfma_f32_16x16x32_bf16 v[82:85], v[46:49], v[180:183], v[82:85]
	v_mfma_f32_16x16x32_bf16 v[78:81], v[54:57], v[180:183], v[78:81]
	v_mfma_f32_16x16x32_bf16 v[66:69], v[46:49], v[188:191], v[66:69]
	v_mfma_f32_16x16x32_bf16 v[62:65], v[54:57], v[188:191], v[62:65]
	v_mfma_f32_16x16x32_bf16 v[34:37], v[46:49], v[196:199], v[34:37]
	v_mfma_f32_16x16x32_bf16 v[30:33], v[54:57], v[196:199], v[30:33]
	v_mfma_f32_16x16x32_bf16 v[18:21], v[46:49], v[204:207], v[18:21]
	v_mfma_f32_16x16x32_bf16 v[14:17], v[54:57], v[204:207], v[14:17]
	v_mfma_f32_16x16x32_bf16 v[82:85], v[50:53], v[184:187], v[82:85]
	v_mfma_f32_16x16x32_bf16 v[78:81], v[58:61], v[184:187], v[78:81]
	v_mfma_f32_16x16x32_bf16 v[66:69], v[50:53], v[192:195], v[66:69]
	v_mfma_f32_16x16x32_bf16 v[62:65], v[58:61], v[192:195], v[62:65]
	v_mfma_f32_16x16x32_bf16 v[34:37], v[50:53], v[200:203], v[34:37]
	v_mfma_f32_16x16x32_bf16 v[30:33], v[58:61], v[200:203], v[30:33]
	v_mfma_f32_16x16x32_bf16 v[18:21], v[50:53], v[208:211], v[18:21]
	v_mfma_f32_16x16x32_bf16 v[14:17], v[58:61], v[208:211], v[14:17]
	s_setprio 0
	s_setprio 1
	v_mfma_f32_16x16x32_bf16 v[42:45], v[160:163], v[188:191], v[42:45]
	v_mfma_f32_16x16x32_bf16 v[38:41], v[172:175], v[188:191], v[38:41]
	v_mfma_f32_16x16x32_bf16 v[26:29], v[160:163], v[196:199], v[26:29]
	v_mfma_f32_16x16x32_bf16 v[22:25], v[172:175], v[196:199], v[22:25]
	v_mfma_f32_16x16x32_bf16 v[10:13], v[160:163], v[204:207], v[10:13]
	v_mfma_f32_16x16x32_bf16 v[6:9], v[172:175], v[204:207], v[6:9]
	v_mfma_f32_16x16x32_bf16 v[46:49], v[160:163], v[180:183], v[74:77]
	v_mfma_f32_16x16x32_bf16 v[50:53], v[172:175], v[180:183], v[70:73]
	v_mfma_f32_16x16x32_bf16 v[42:45], v[168:171], v[192:195], v[42:45]
	v_mfma_f32_16x16x32_bf16 v[38:41], v[176:179], v[192:195], v[38:41]
	v_mfma_f32_16x16x32_bf16 v[26:29], v[168:171], v[200:203], v[26:29]
	v_mfma_f32_16x16x32_bf16 v[22:25], v[176:179], v[200:203], v[22:25]
	v_mfma_f32_16x16x32_bf16 v[10:13], v[168:171], v[208:211], v[10:13]
	v_mfma_f32_16x16x32_bf16 v[6:9], v[176:179], v[208:211], v[6:9]
	v_mfma_f32_16x16x32_bf16 v[46:49], v[168:171], v[184:187], v[46:49]
	v_mfma_f32_16x16x32_bf16 v[50:53], v[176:179], v[184:187], v[50:53]
	s_barrier
	s_setprio 0
	s_add_i32 s60, 0, 0x18000
	v_add_u32_e32 v0, s60, v164
	s_add_i32 s61, 0, 0x1c000
	ds_read_b128 v[54:57], v0
	ds_read_b128 v[58:61], v0 offset:1024
	ds_read_b128 v[70:73], v0 offset:2048
	ds_read_b128 v[74:77], v0 offset:3072
	v_add_u32_e32 v0, s61, v164
	ds_read_b128 v[160:163], v0
	ds_read_b128 v[168:171], v0 offset:1024
	ds_read_b128 v[172:175], v0 offset:2048
	ds_read_b128 v[176:179], v0 offset:3072
	s_add_u32 s30, s30, 0x40000
	s_addc_u32 s31, s31, 0
	s_mov_b32 m0, s38
	v_lshl_add_u64 v[222:223], s[30:31], 0, v[2:3]
	ds_read_b128 v[180:183], v166 offset:32768
	ds_read_b128 v[184:187], v166 offset:33792
	ds_read_b128 v[188:191], v166 offset:34816
	ds_read_b128 v[192:195], v166 offset:35840
	ds_read_b128 v[196:199], v166 offset:36864
	ds_read_b128 v[200:203], v166 offset:37888
	ds_read_b128 v[204:207], v166 offset:38912
	ds_read_b128 v[208:211], v166 offset:39936
	global_load_lds_dwordx4 v[222:223], off
	v_lshl_add_u64 v[222:223], s[30:31], 0, v[152:153]
	s_mov_b32 m0, s39
	s_nop 0
	global_load_lds_dwordx4 v[222:223], off
	s_waitcnt vmcnt(8)
	s_waitcnt lgkmcnt(0)
	s_barrier
	s_setprio 1
	s_waitcnt lgkmcnt(0)
	v_mfma_f32_16x16x32_bf16 v[146:149], v[54:57], v[180:183], v[146:149]
	v_mfma_f32_16x16x32_bf16 v[142:145], v[70:73], v[180:183], v[142:145]
	v_mfma_f32_16x16x32_bf16 v[130:133], v[54:57], v[188:191], v[130:133]
	v_mfma_f32_16x16x32_bf16 v[126:129], v[70:73], v[188:191], v[126:129]
	v_mfma_f32_16x16x32_bf16 v[114:117], v[54:57], v[196:199], v[114:117]
	v_mfma_f32_16x16x32_bf16 v[110:113], v[70:73], v[196:199], v[110:113]
	v_mfma_f32_16x16x32_bf16 v[98:101], v[54:57], v[204:207], v[98:101]
	v_mfma_f32_16x16x32_bf16 v[94:97], v[70:73], v[204:207], v[94:97]
	v_mfma_f32_16x16x32_bf16 v[146:149], v[58:61], v[184:187], v[146:149]
	v_mfma_f32_16x16x32_bf16 v[142:145], v[74:77], v[184:187], v[142:145]
	v_mfma_f32_16x16x32_bf16 v[130:133], v[58:61], v[192:195], v[130:133]
	v_mfma_f32_16x16x32_bf16 v[126:129], v[74:77], v[192:195], v[126:129]
	v_mfma_f32_16x16x32_bf16 v[114:117], v[58:61], v[200:203], v[114:117]
	v_mfma_f32_16x16x32_bf16 v[110:113], v[74:77], v[200:203], v[110:113]
	v_mfma_f32_16x16x32_bf16 v[98:101], v[58:61], v[208:211], v[98:101]
	v_mfma_f32_16x16x32_bf16 v[94:97], v[74:77], v[208:211], v[94:97]
	s_setprio 0
	s_setprio 1
	v_mfma_f32_16x16x32_bf16 v[138:141], v[160:163], v[180:183], v[138:141]
	v_mfma_f32_16x16x32_bf16 v[134:137], v[172:175], v[180:183], v[134:137]
	v_mfma_f32_16x16x32_bf16 v[122:125], v[160:163], v[188:191], v[122:125]
	v_mfma_f32_16x16x32_bf16 v[118:121], v[172:175], v[188:191], v[118:121]
	v_mfma_f32_16x16x32_bf16 v[106:109], v[160:163], v[196:199], v[106:109]
	v_mfma_f32_16x16x32_bf16 v[102:105], v[172:175], v[196:199], v[102:105]
	v_mfma_f32_16x16x32_bf16 v[90:93], v[160:163], v[204:207], v[90:93]
	v_mfma_f32_16x16x32_bf16 v[86:89], v[172:175], v[204:207], v[86:89]
	v_mfma_f32_16x16x32_bf16 v[138:141], v[168:171], v[184:187], v[138:141]
	v_mfma_f32_16x16x32_bf16 v[134:137], v[176:179], v[184:187], v[134:137]
	v_mfma_f32_16x16x32_bf16 v[122:125], v[168:171], v[192:195], v[122:125]
	v_mfma_f32_16x16x32_bf16 v[118:121], v[176:179], v[192:195], v[118:121]
	v_mfma_f32_16x16x32_bf16 v[106:109], v[168:171], v[200:203], v[106:109]
	v_mfma_f32_16x16x32_bf16 v[102:105], v[176:179], v[200:203], v[102:105]
	v_mfma_f32_16x16x32_bf16 v[90:93], v[168:171], v[208:211], v[90:93]
	v_mfma_f32_16x16x32_bf16 v[86:89], v[176:179], v[208:211], v[86:89]
	s_barrier
	s_setprio 0
	s_add_i32 s30, s60, s35
	v_lshl_add_u64 v[212:213], v[212:213], 0, s[50:51]
	s_mov_b32 m0, s30
	ds_read_b128 v[180:183], v166 offset:49152
	ds_read_b128 v[184:187], v166 offset:50176
	ds_read_b128 v[188:191], v166 offset:51200
	ds_read_b128 v[192:195], v166 offset:52224
	ds_read_b128 v[196:199], v166 offset:53248
	ds_read_b128 v[200:203], v166 offset:54272
	ds_read_b128 v[204:207], v166 offset:55296
	ds_read_b128 v[208:211], v166 offset:56320
	global_load_lds_dwordx4 v[212:213], off
	s_add_i32 m0, s30, 0x2000
	s_add_u32 s28, s28, 0x40080
	v_lshl_add_u64 v[212:213], v[214:215], 0, s[50:51]
	s_addc_u32 s29, s29, 0
	s_add_i32 s30, s61, s35
	global_load_lds_dwordx4 v[212:213], off
	v_lshl_add_u64 v[212:213], s[28:29], 0, v[150:151]
	s_mov_b32 m0, s30
	s_nop 0
	global_load_lds_dwordx4 v[212:213], off
	v_lshl_add_u64 v[212:213], s[28:29], 0, v[154:155]
	s_add_i32 m0, s30, 0x2000
	s_nop 0
	global_load_lds_dwordx4 v[212:213], off
	v_lshl_add_u64 v[212:213], v[216:217], 0, s[50:51]
	s_mov_b32 m0, s41
	s_nop 0
	global_load_lds_dwordx4 v[212:213], off
	v_lshl_add_u64 v[212:213], v[220:221], 0, s[50:51]
	s_mov_b32 m0, s42
	s_nop 0
	global_load_lds_dwordx4 v[212:213], off
	s_waitcnt vmcnt(8)
	s_waitcnt lgkmcnt(0)
	s_barrier
	s_setprio 1
	s_waitcnt lgkmcnt(0)
	v_mfma_f32_16x16x32_bf16 v[82:85], v[54:57], v[180:183], v[82:85]
	v_mfma_f32_16x16x32_bf16 v[78:81], v[70:73], v[180:183], v[78:81]
	v_mfma_f32_16x16x32_bf16 v[66:69], v[54:57], v[188:191], v[66:69]
	v_mfma_f32_16x16x32_bf16 v[62:65], v[70:73], v[188:191], v[62:65]
	v_mfma_f32_16x16x32_bf16 v[34:37], v[54:57], v[196:199], v[34:37]
	v_mfma_f32_16x16x32_bf16 v[30:33], v[70:73], v[196:199], v[30:33]
	v_mfma_f32_16x16x32_bf16 v[18:21], v[54:57], v[204:207], v[18:21]
	v_mfma_f32_16x16x32_bf16 v[14:17], v[70:73], v[204:207], v[14:17]
	v_mfma_f32_16x16x32_bf16 v[82:85], v[58:61], v[184:187], v[82:85]
	v_mfma_f32_16x16x32_bf16 v[78:81], v[74:77], v[184:187], v[78:81]
	v_mfma_f32_16x16x32_bf16 v[66:69], v[58:61], v[192:195], v[66:69]
	v_mfma_f32_16x16x32_bf16 v[62:65], v[74:77], v[192:195], v[62:65]
	v_mfma_f32_16x16x32_bf16 v[34:37], v[58:61], v[200:203], v[34:37]
	v_mfma_f32_16x16x32_bf16 v[30:33], v[74:77], v[200:203], v[30:33]
	v_mfma_f32_16x16x32_bf16 v[18:21], v[58:61], v[208:211], v[18:21]
	v_mfma_f32_16x16x32_bf16 v[14:17], v[74:77], v[208:211], v[14:17]
	s_setprio 0
	s_setprio 1
	v_mfma_f32_16x16x32_bf16 v[46:49], v[160:163], v[180:183], v[46:49]
	v_mfma_f32_16x16x32_bf16 v[74:77], v[168:171], v[184:187], v[46:49]
	v_mfma_f32_16x16x32_bf16 v[46:49], v[172:175], v[180:183], v[50:53]
	v_mfma_f32_16x16x32_bf16 v[42:45], v[160:163], v[188:191], v[42:45]
	v_mfma_f32_16x16x32_bf16 v[38:41], v[172:175], v[188:191], v[38:41]
	v_mfma_f32_16x16x32_bf16 v[26:29], v[160:163], v[196:199], v[26:29]
	v_mfma_f32_16x16x32_bf16 v[22:25], v[172:175], v[196:199], v[22:25]
	v_mfma_f32_16x16x32_bf16 v[10:13], v[160:163], v[204:207], v[10:13]
	v_mfma_f32_16x16x32_bf16 v[6:9], v[172:175], v[204:207], v[6:9]
	v_mfma_f32_16x16x32_bf16 v[70:73], v[176:179], v[184:187], v[46:49]
	v_mfma_f32_16x16x32_bf16 v[42:45], v[168:171], v[192:195], v[42:45]
	v_mfma_f32_16x16x32_bf16 v[38:41], v[176:179], v[192:195], v[38:41]
	v_mfma_f32_16x16x32_bf16 v[26:29], v[168:171], v[200:203], v[26:29]
	v_mfma_f32_16x16x32_bf16 v[22:25], v[176:179], v[200:203], v[22:25]
	v_mfma_f32_16x16x32_bf16 v[10:13], v[168:171], v[208:211], v[10:13]
	v_mfma_f32_16x16x32_bf16 v[6:9], v[176:179], v[208:211], v[6:9]
	s_barrier
	s_setprio 0
	s_add_i32 s59, s59, 2
	s_add_u32 s26, s26, 0x100
	s_addc_u32 s27, s27, 0
	s_add_u32 s48, s48, 0x100
	s_addc_u32 s58, s58, 0
	s_cmp_gt_u32 s59, 13
	s_cbranch_scc0 .LBB0_205
	s_and_b64 vcc, exec, s[14:15]
	s_cbranch_vccz .LBB0_208
	s_barrier

.LBB0_301:
	s_add_i32 s80, s38, 2
	s_add_u32 s81, s36, 0x80
	s_addc_u32 s39, s37, 0
	s_add_i32 s84, 0, 0x10000
	s_cmp_eq_u32 s31, s38
	s_cselect_b32 s39, s27, s39
	s_cselect_b32 s38, s26, s81
	s_waitcnt lgkmcnt(0)
	s_cselect_b32 s83, s29, s79
	s_cselect_b32 s82, s28, s78
	s_add_i32 s81, 0, 0x14000
	v_add_u32_e32 v146, s84, v206
	v_add_u32_e32 v162, s81, v206
	ds_read_b128 v[134:137], v146
	ds_read_b128 v[138:141], v146 offset:1024
	ds_read_b128 v[142:145], v146 offset:2048
	ds_read_b128 v[146:149], v146 offset:3072
	ds_read_b128 v[150:153], v162
	ds_read_b128 v[154:157], v162 offset:1024
	ds_read_b128 v[158:161], v162 offset:2048
	ds_read_b128 v[162:165], v162 offset:3072
	v_lshl_add_u64 v[202:203], s[36:37], 0, v[182:183]
	s_add_i32 m0, s44, 0xc000
	ds_read_b128 v[166:169], v209
	ds_read_b128 v[170:173], v209 offset:1024
	ds_read_b128 v[174:177], v209 offset:2048
	ds_read_b128 v[178:181], v209 offset:3072
	ds_read_b128 v[186:189], v209 offset:4096
	ds_read_b128 v[190:193], v209 offset:5120
	ds_read_b128 v[194:197], v209 offset:6144
	ds_read_b128 v[198:201], v209 offset:7168
	global_load_lds_dwordx4 v[202:203], off
	v_lshl_add_u64 v[202:203], s[36:37], 0, v[184:185]
	s_add_i32 m0, s44, 0xe000
	s_nop 0
	global_load_lds_dwordx4 v[202:203], off
	s_waitcnt vmcnt(8)
	s_waitcnt lgkmcnt(0)
	s_barrier
	s_setprio 1
	s_waitcnt lgkmcnt(0)
	v_mfma_f32_16x16x32_bf16 v[130:133], v[134:137], v[166:169], v[130:133]
	v_mfma_f32_16x16x32_bf16 v[126:129], v[142:145], v[166:169], v[126:129]
	v_mfma_f32_16x16x32_bf16 v[114:117], v[134:137], v[174:177], v[114:117]
	v_mfma_f32_16x16x32_bf16 v[110:113], v[142:145], v[174:177], v[110:113]
	v_mfma_f32_16x16x32_bf16 v[98:101], v[134:137], v[186:189], v[98:101]
	v_mfma_f32_16x16x32_bf16 v[94:97], v[142:145], v[186:189], v[94:97]
	v_mfma_f32_16x16x32_bf16 v[82:85], v[134:137], v[194:197], v[82:85]
	v_mfma_f32_16x16x32_bf16 v[78:81], v[142:145], v[194:197], v[78:81]
	v_mfma_f32_16x16x32_bf16 v[130:133], v[138:141], v[170:173], v[130:133]
	v_mfma_f32_16x16x32_bf16 v[126:129], v[146:149], v[170:173], v[126:129]
	v_mfma_f32_16x16x32_bf16 v[114:117], v[138:141], v[178:181], v[114:117]
	v_mfma_f32_16x16x32_bf16 v[110:113], v[146:149], v[178:181], v[110:113]
	v_mfma_f32_16x16x32_bf16 v[98:101], v[138:141], v[190:193], v[98:101]
	v_mfma_f32_16x16x32_bf16 v[94:97], v[146:149], v[190:193], v[94:97]
	v_mfma_f32_16x16x32_bf16 v[82:85], v[138:141], v[198:201], v[82:85]
	v_mfma_f32_16x16x32_bf16 v[78:81], v[146:149], v[198:201], v[78:81]
	s_setprio 0
	s_setprio 1
	v_mfma_f32_16x16x32_bf16 v[122:125], v[150:153], v[166:169], v[122:125]
	v_mfma_f32_16x16x32_bf16 v[118:121], v[158:161], v[166:169], v[118:121]
	v_mfma_f32_16x16x32_bf16 v[106:109], v[150:153], v[174:177], v[106:109]
	v_mfma_f32_16x16x32_bf16 v[102:105], v[158:161], v[174:177], v[102:105]
	v_mfma_f32_16x16x32_bf16 v[90:93], v[150:153], v[186:189], v[90:93]
	v_mfma_f32_16x16x32_bf16 v[86:89], v[158:161], v[186:189], v[86:89]
	v_mfma_f32_16x16x32_bf16 v[74:77], v[150:153], v[194:197], v[74:77]
	v_mfma_f32_16x16x32_bf16 v[70:73], v[158:161], v[194:197], v[70:73]
	v_mfma_f32_16x16x32_bf16 v[122:125], v[154:157], v[170:173], v[122:125]
	v_mfma_f32_16x16x32_bf16 v[118:121], v[162:165], v[170:173], v[118:121]
	v_mfma_f32_16x16x32_bf16 v[106:109], v[154:157], v[178:181], v[106:109]
	v_mfma_f32_16x16x32_bf16 v[102:105], v[162:165], v[178:181], v[102:105]
	v_mfma_f32_16x16x32_bf16 v[90:93], v[154:157], v[190:193], v[90:93]
	v_mfma_f32_16x16x32_bf16 v[86:89], v[162:165], v[190:193], v[86:89]
	v_mfma_f32_16x16x32_bf16 v[74:77], v[154:157], v[198:201], v[74:77]
	v_mfma_f32_16x16x32_bf16 v[70:73], v[162:165], v[198:201], v[70:73]
	s_barrier
	s_setprio 0
	s_add_i32 s84, s84, s43
	v_lshl_add_u64 v[202:203], s[82:83], 0, v[0:1]
	s_mov_b32 m0, s84
	ds_read_b128 v[166:169], v209 offset:16384
	ds_read_b128 v[170:173], v209 offset:17408
	ds_read_b128 v[174:177], v209 offset:18432
	ds_read_b128 v[178:181], v209 offset:19456
	ds_read_b128 v[186:189], v209 offset:20480
	ds_read_b128 v[190:193], v209 offset:21504
	ds_read_b128 v[194:197], v209 offset:22528
	ds_read_b128 v[198:201], v209 offset:23552
	global_load_lds_dwordx4 v[202:203], off
	s_add_i32 m0, s84, 0x2000
	v_lshl_add_u64 v[204:205], s[82:83], 0, v[2:3]
	s_add_u32 s82, s82, s48
	s_addc_u32 s83, s83, 0
	s_add_i32 s81, s81, s43
	global_load_lds_dwordx4 v[204:205], off
	v_lshl_add_u64 v[210:211], s[82:83], 0, v[0:1]
	s_mov_b32 m0, s81
	v_lshl_add_u64 v[212:213], s[82:83], 0, v[2:3]
	global_load_lds_dwordx4 v[210:211], off
	s_add_i32 m0, s81, 0x2000
	v_lshl_add_u64 v[214:215], s[38:39], 0, v[0:1]
	global_load_lds_dwordx4 v[212:213], off
	s_mov_b32 m0, s44
	v_lshl_add_u64 v[216:217], s[38:39], 0, v[2:3]
	global_load_lds_dwordx4 v[214:215], off
	s_mov_b32 m0, s45
	s_nop 0
	global_load_lds_dwordx4 v[216:217], off
	s_waitcnt vmcnt(8)
	s_waitcnt lgkmcnt(0)
	s_barrier
	s_setprio 1
	s_waitcnt lgkmcnt(0)
	v_mfma_f32_16x16x32_bf16 v[66:69], v[134:137], v[166:169], v[66:69]
	v_mfma_f32_16x16x32_bf16 v[62:65], v[142:145], v[166:169], v[62:65]
	v_mfma_f32_16x16x32_bf16 v[50:53], v[134:137], v[174:177], v[50:53]
	v_mfma_f32_16x16x32_bf16 v[46:49], v[142:145], v[174:177], v[46:49]
	v_mfma_f32_16x16x32_bf16 v[34:37], v[134:137], v[186:189], v[34:37]
	v_mfma_f32_16x16x32_bf16 v[30:33], v[142:145], v[186:189], v[30:33]
	v_mfma_f32_16x16x32_bf16 v[18:21], v[134:137], v[194:197], v[18:21]
	v_mfma_f32_16x16x32_bf16 v[14:17], v[142:145], v[194:197], v[14:17]
	v_mfma_f32_16x16x32_bf16 v[66:69], v[138:141], v[170:173], v[66:69]
	v_mfma_f32_16x16x32_bf16 v[62:65], v[146:149], v[170:173], v[62:65]
	v_mfma_f32_16x16x32_bf16 v[50:53], v[138:141], v[178:181], v[50:53]
	v_mfma_f32_16x16x32_bf16 v[46:49], v[146:149], v[178:181], v[46:49]
	v_mfma_f32_16x16x32_bf16 v[34:37], v[138:141], v[190:193], v[34:37]
	v_mfma_f32_16x16x32_bf16 v[30:33], v[146:149], v[190:193], v[30:33]
	v_mfma_f32_16x16x32_bf16 v[18:21], v[138:141], v[198:201], v[18:21]
	v_mfma_f32_16x16x32_bf16 v[14:17], v[146:149], v[198:201], v[14:17]
	s_setprio 0
	s_setprio 1
	v_mfma_f32_16x16x32_bf16 v[58:61], v[150:153], v[166:169], v[58:61]
	v_mfma_f32_16x16x32_bf16 v[54:57], v[158:161], v[166:169], v[54:57]
	v_mfma_f32_16x16x32_bf16 v[42:45], v[150:153], v[174:177], v[42:45]
	v_mfma_f32_16x16x32_bf16 v[38:41], v[158:161], v[174:177], v[38:41]
	v_mfma_f32_16x16x32_bf16 v[26:29], v[150:153], v[186:189], v[26:29]
	v_mfma_f32_16x16x32_bf16 v[22:25], v[158:161], v[186:189], v[22:25]
	v_mfma_f32_16x16x32_bf16 v[10:13], v[150:153], v[194:197], v[10:13]
	v_mfma_f32_16x16x32_bf16 v[6:9], v[158:161], v[194:197], v[6:9]
	v_mfma_f32_16x16x32_bf16 v[58:61], v[154:157], v[170:173], v[58:61]
	v_mfma_f32_16x16x32_bf16 v[54:57], v[162:165], v[170:173], v[54:57]
	v_mfma_f32_16x16x32_bf16 v[42:45], v[154:157], v[178:181], v[42:45]
	v_mfma_f32_16x16x32_bf16 v[38:41], v[162:165], v[178:181], v[38:41]
	v_mfma_f32_16x16x32_bf16 v[26:29], v[154:157], v[190:193], v[26:29]
	v_mfma_f32_16x16x32_bf16 v[22:25], v[162:165], v[190:193], v[22:25]
	v_mfma_f32_16x16x32_bf16 v[10:13], v[154:157], v[198:201], v[10:13]
	v_mfma_f32_16x16x32_bf16 v[6:9], v[162:165], v[198:201], v[6:9]
	s_barrier
	s_setprio 0
	s_add_i32 s81, 0, 0x18000
	s_add_i32 s82, 0, 0x1c000
	v_add_u32_e32 v146, s81, v206
	v_add_u32_e32 v162, s82, v206
	ds_read_b128 v[134:137], v146
	ds_read_b128 v[138:141], v146 offset:1024
	ds_read_b128 v[142:145], v146 offset:2048
	ds_read_b128 v[146:149], v146 offset:3072
	ds_read_b128 v[150:153], v162
	ds_read_b128 v[154:157], v162 offset:1024
	ds_read_b128 v[158:161], v162 offset:2048
	ds_read_b128 v[162:165], v162 offset:3072
	s_add_u32 s38, s38, s48
	s_addc_u32 s39, s39, 0
	s_mov_b32 m0, s58
	v_lshl_add_u64 v[220:221], s[38:39], 0, v[0:1]
	ds_read_b128 v[166:169], v209 offset:32768
	ds_read_b128 v[170:173], v209 offset:33792
	ds_read_b128 v[174:177], v209 offset:34816
	ds_read_b128 v[178:181], v209 offset:35840
	ds_read_b128 v[186:189], v209 offset:36864
	ds_read_b128 v[190:193], v209 offset:37888
	ds_read_b128 v[194:197], v209 offset:38912
	ds_read_b128 v[198:201], v209 offset:39936
	global_load_lds_dwordx4 v[220:221], off
	v_lshl_add_u64 v[220:221], s[38:39], 0, v[2:3]
	s_mov_b32 m0, s59
	s_nop 0
	global_load_lds_dwordx4 v[220:221], off
	s_waitcnt vmcnt(8)
	s_waitcnt lgkmcnt(0)
	s_barrier
	s_setprio 1
	s_waitcnt lgkmcnt(0)
	v_mfma_f32_16x16x32_bf16 v[130:133], v[134:137], v[166:169], v[130:133]
	v_mfma_f32_16x16x32_bf16 v[126:129], v[142:145], v[166:169], v[126:129]
	v_mfma_f32_16x16x32_bf16 v[114:117], v[134:137], v[174:177], v[114:117]
	v_mfma_f32_16x16x32_bf16 v[110:113], v[142:145], v[174:177], v[110:113]
	v_mfma_f32_16x16x32_bf16 v[98:101], v[134:137], v[186:189], v[98:101]
	v_mfma_f32_16x16x32_bf16 v[94:97], v[142:145], v[186:189], v[94:97]
	v_mfma_f32_16x16x32_bf16 v[82:85], v[134:137], v[194:197], v[82:85]
	v_mfma_f32_16x16x32_bf16 v[78:81], v[142:145], v[194:197], v[78:81]
	v_mfma_f32_16x16x32_bf16 v[130:133], v[138:141], v[170:173], v[130:133]
	v_mfma_f32_16x16x32_bf16 v[126:129], v[146:149], v[170:173], v[126:129]
	v_mfma_f32_16x16x32_bf16 v[114:117], v[138:141], v[178:181], v[114:117]
	v_mfma_f32_16x16x32_bf16 v[110:113], v[146:149], v[178:181], v[110:113]
	v_mfma_f32_16x16x32_bf16 v[98:101], v[138:141], v[190:193], v[98:101]
	v_mfma_f32_16x16x32_bf16 v[94:97], v[146:149], v[190:193], v[94:97]
	v_mfma_f32_16x16x32_bf16 v[82:85], v[138:141], v[198:201], v[82:85]
	v_mfma_f32_16x16x32_bf16 v[78:81], v[146:149], v[198:201], v[78:81]
	s_setprio 0
	s_setprio 1
	v_mfma_f32_16x16x32_bf16 v[122:125], v[150:153], v[166:169], v[122:125]
	v_mfma_f32_16x16x32_bf16 v[118:121], v[158:161], v[166:169], v[118:121]
	v_mfma_f32_16x16x32_bf16 v[106:109], v[150:153], v[174:177], v[106:109]
	v_mfma_f32_16x16x32_bf16 v[102:105], v[158:161], v[174:177], v[102:105]
	v_mfma_f32_16x16x32_bf16 v[90:93], v[150:153], v[186:189], v[90:93]
	v_mfma_f32_16x16x32_bf16 v[86:89], v[158:161], v[186:189], v[86:89]
	v_mfma_f32_16x16x32_bf16 v[74:77], v[150:153], v[194:197], v[74:77]
	v_mfma_f32_16x16x32_bf16 v[70:73], v[158:161], v[194:197], v[70:73]
	v_mfma_f32_16x16x32_bf16 v[122:125], v[154:157], v[170:173], v[122:125]
	v_mfma_f32_16x16x32_bf16 v[118:121], v[162:165], v[170:173], v[118:121]
	v_mfma_f32_16x16x32_bf16 v[106:109], v[154:157], v[178:181], v[106:109]
	v_mfma_f32_16x16x32_bf16 v[102:105], v[162:165], v[178:181], v[102:105]
	v_mfma_f32_16x16x32_bf16 v[90:93], v[154:157], v[190:193], v[90:93]
	v_mfma_f32_16x16x32_bf16 v[86:89], v[162:165], v[190:193], v[86:89]
	v_mfma_f32_16x16x32_bf16 v[74:77], v[154:157], v[198:201], v[74:77]
	v_mfma_f32_16x16x32_bf16 v[70:73], v[162:165], v[198:201], v[70:73]
	s_barrier
	s_setprio 0
	s_add_i32 s38, s81, s43
	v_lshl_add_u64 v[202:203], v[202:203], 0, s[50:51]
	s_mov_b32 m0, s38
	ds_read_b128 v[166:169], v209 offset:49152
	ds_read_b128 v[170:173], v209 offset:50176
	ds_read_b128 v[174:177], v209 offset:51200
	ds_read_b128 v[178:181], v209 offset:52224
	ds_read_b128 v[186:189], v209 offset:53248
	ds_read_b128 v[190:193], v209 offset:54272
	ds_read_b128 v[194:197], v209 offset:55296
	ds_read_b128 v[198:201], v209 offset:56320
	global_load_lds_dwordx4 v[202:203], off
	v_lshl_add_u64 v[202:203], v[204:205], 0, s[50:51]
	s_add_i32 m0, s38, 0x2000
	s_add_i32 s38, s82, s43
	global_load_lds_dwordx4 v[202:203], off
	v_lshl_add_u64 v[202:203], v[210:211], 0, s[50:51]
	s_mov_b32 m0, s38
	s_nop 0
	global_load_lds_dwordx4 v[202:203], off
	v_lshl_add_u64 v[202:203], v[212:213], 0, s[50:51]
	s_add_i32 m0, s38, 0x2000
	s_nop 0
	global_load_lds_dwordx4 v[202:203], off
	v_lshl_add_u64 v[202:203], v[214:215], 0, s[50:51]
	s_mov_b32 m0, s63
	s_nop 0
	global_load_lds_dwordx4 v[202:203], off
	v_lshl_add_u64 v[202:203], v[216:217], 0, s[50:51]
	s_mov_b32 m0, s64
	s_nop 0
	global_load_lds_dwordx4 v[202:203], off
	s_waitcnt vmcnt(8)
	s_waitcnt lgkmcnt(0)
	s_barrier
	s_setprio 1
	s_waitcnt lgkmcnt(0)
	v_mfma_f32_16x16x32_bf16 v[66:69], v[134:137], v[166:169], v[66:69]
	v_mfma_f32_16x16x32_bf16 v[62:65], v[142:145], v[166:169], v[62:65]
	v_mfma_f32_16x16x32_bf16 v[50:53], v[134:137], v[174:177], v[50:53]
	v_mfma_f32_16x16x32_bf16 v[46:49], v[142:145], v[174:177], v[46:49]
	v_mfma_f32_16x16x32_bf16 v[34:37], v[134:137], v[186:189], v[34:37]
	v_mfma_f32_16x16x32_bf16 v[30:33], v[142:145], v[186:189], v[30:33]
	v_mfma_f32_16x16x32_bf16 v[18:21], v[134:137], v[194:197], v[18:21]
	v_mfma_f32_16x16x32_bf16 v[14:17], v[142:145], v[194:197], v[14:17]
	v_mfma_f32_16x16x32_bf16 v[66:69], v[138:141], v[170:173], v[66:69]
	v_mfma_f32_16x16x32_bf16 v[62:65], v[146:149], v[170:173], v[62:65]
	v_mfma_f32_16x16x32_bf16 v[50:53], v[138:141], v[178:181], v[50:53]
	v_mfma_f32_16x16x32_bf16 v[46:49], v[146:149], v[178:181], v[46:49]
	v_mfma_f32_16x16x32_bf16 v[34:37], v[138:141], v[190:193], v[34:37]
	v_mfma_f32_16x16x32_bf16 v[30:33], v[146:149], v[190:193], v[30:33]
	v_mfma_f32_16x16x32_bf16 v[18:21], v[138:141], v[198:201], v[18:21]
	v_mfma_f32_16x16x32_bf16 v[14:17], v[146:149], v[198:201], v[14:17]
	s_setprio 0
	s_setprio 1
	v_mfma_f32_16x16x32_bf16 v[58:61], v[150:153], v[166:169], v[58:61]
	v_mfma_f32_16x16x32_bf16 v[54:57], v[158:161], v[166:169], v[54:57]
	v_mfma_f32_16x16x32_bf16 v[42:45], v[150:153], v[174:177], v[42:45]
	v_mfma_f32_16x16x32_bf16 v[38:41], v[158:161], v[174:177], v[38:41]
	v_mfma_f32_16x16x32_bf16 v[26:29], v[150:153], v[186:189], v[26:29]
	v_mfma_f32_16x16x32_bf16 v[22:25], v[158:161], v[186:189], v[22:25]
	v_mfma_f32_16x16x32_bf16 v[10:13], v[150:153], v[194:197], v[10:13]
	v_mfma_f32_16x16x32_bf16 v[6:9], v[158:161], v[194:197], v[6:9]
	v_mfma_f32_16x16x32_bf16 v[58:61], v[154:157], v[170:173], v[58:61]
	v_mfma_f32_16x16x32_bf16 v[54:57], v[162:165], v[170:173], v[54:57]
	v_mfma_f32_16x16x32_bf16 v[42:45], v[154:157], v[178:181], v[42:45]
	v_mfma_f32_16x16x32_bf16 v[38:41], v[162:165], v[178:181], v[38:41]
	v_mfma_f32_16x16x32_bf16 v[26:29], v[154:157], v[190:193], v[26:29]
	v_mfma_f32_16x16x32_bf16 v[22:25], v[162:165], v[190:193], v[22:25]
	v_mfma_f32_16x16x32_bf16 v[10:13], v[154:157], v[198:201], v[10:13]
	v_mfma_f32_16x16x32_bf16 v[6:9], v[162:165], v[198:201], v[6:9]
	s_barrier
	s_setprio 0
	s_add_u32 s36, s36, 0x100
	s_addc_u32 s37, s37, 0
	s_add_u32 s78, s78, 0x100
	s_addc_u32 s79, s79, 0
	s_cmp_ge_i32 s80, s25
	s_mov_b32 s38, s80
	s_cbranch_scc0 .LBB0_301
	s_load_dwordx2 s[82:83], s[54:55], 0xe0
	v_readlane_b32 s80, v253, 39
	v_readlane_b32 s84, v253, 44
	v_readlane_b32 s81, v253, 40
	s_and_b64 vcc, exec, s[20:21]
	s_cbranch_vccz .LBB0_304

.LBB0_347:
	s_add_u32 s34, s8, 0xfffc0080
	s_addc_u32 s35, s9, -1
	s_add_i32 s41, 0, 0x10000
	s_cmp_eq_u32 s39, 12
	s_cselect_b32 s37, s3, s35
	s_cselect_b32 s36, s7, s34
	v_add_u32_e32 v0, s41, v243
	s_cselect_b32 s35, s25, s38
	s_cselect_b32 s34, s27, s33
	s_add_i32 s44, 0, 0x14000
	ds_read_b128 v[40:43], v0
	ds_read_b128 v[44:47], v0 offset:1024
	ds_read_b128 v[48:51], v0 offset:2048
	ds_read_b128 v[52:55], v0 offset:3072
	v_add_u32_e32 v0, s44, v243
	s_waitcnt vmcnt(0)
	ds_read_b128 v[64:67], v0
	ds_read_b128 v[68:71], v0 offset:1024
	ds_read_b128 v[80:83], v0 offset:2048
	ds_read_b128 v[84:87], v0 offset:3072
	v_lshl_add_u64 v[2:3], s[8:9], 0, v[198:199]
	s_add_i32 m0, s61, 0xc000
	ds_read_b128 v[88:91], v244
	ds_read_b128 v[92:95], v244 offset:1024
	ds_read_b128 v[176:179], v244 offset:2048
	ds_read_b128 v[180:183], v244 offset:3072
	ds_read_b128 v[202:205], v244 offset:4096
	ds_read_b128 v[206:209], v244 offset:5120
	ds_read_b128 v[210:213], v244 offset:6144
	ds_read_b128 v[220:223], v244 offset:7168
	global_load_lds_dwordx4 v[2:3], off
	v_lshl_add_u64 v[2:3], s[8:9], 0, v[200:201]
	s_add_i32 m0, s61, 0xe000
	s_nop 0
	global_load_lds_dwordx4 v[2:3], off
	s_waitcnt vmcnt(8)
	s_waitcnt lgkmcnt(0)
	s_barrier
	s_setprio 1
	s_waitcnt lgkmcnt(0)
	v_mfma_f32_16x16x32_bf16 v[172:175], v[40:43], v[88:91], v[172:175]
	v_mfma_f32_16x16x32_bf16 v[168:171], v[48:51], v[88:91], v[168:171]
	v_mfma_f32_16x16x32_bf16 v[156:159], v[40:43], v[176:179], v[156:159]
	v_mfma_f32_16x16x32_bf16 v[152:155], v[48:51], v[176:179], v[152:155]
	v_mfma_f32_16x16x32_bf16 v[140:143], v[40:43], v[202:205], v[140:143]
	v_mfma_f32_16x16x32_bf16 v[136:139], v[48:51], v[202:205], v[136:139]
	v_mfma_f32_16x16x32_bf16 v[124:127], v[40:43], v[210:213], v[124:127]
	v_mfma_f32_16x16x32_bf16 v[120:123], v[48:51], v[210:213], v[120:123]
	v_mfma_f32_16x16x32_bf16 v[172:175], v[44:47], v[92:95], v[172:175]
	v_mfma_f32_16x16x32_bf16 v[168:171], v[52:55], v[92:95], v[168:171]
	v_mfma_f32_16x16x32_bf16 v[156:159], v[44:47], v[180:183], v[156:159]
	v_mfma_f32_16x16x32_bf16 v[152:155], v[52:55], v[180:183], v[152:155]
	v_mfma_f32_16x16x32_bf16 v[140:143], v[44:47], v[206:209], v[140:143]
	v_mfma_f32_16x16x32_bf16 v[136:139], v[52:55], v[206:209], v[136:139]
	v_mfma_f32_16x16x32_bf16 v[124:127], v[44:47], v[220:223], v[124:127]
	v_mfma_f32_16x16x32_bf16 v[120:123], v[52:55], v[220:223], v[120:123]
	s_setprio 0
	s_setprio 1
	v_mfma_f32_16x16x32_bf16 v[164:167], v[64:67], v[88:91], v[164:167]
	v_mfma_f32_16x16x32_bf16 v[88:91], v[80:83], v[88:91], v[160:163]
	v_mfma_f32_16x16x32_bf16 v[144:147], v[80:83], v[176:179], v[144:147]
	v_mfma_f32_16x16x32_bf16 v[132:135], v[64:67], v[202:205], v[132:135]
	v_mfma_f32_16x16x32_bf16 v[128:131], v[80:83], v[202:205], v[128:131]
	v_mfma_f32_16x16x32_bf16 v[116:119], v[64:67], v[210:213], v[116:119]
	v_mfma_f32_16x16x32_bf16 v[112:115], v[80:83], v[210:213], v[112:115]
	v_mfma_f32_16x16x32_bf16 v[164:167], v[68:71], v[92:95], v[164:167]
	v_mfma_f32_16x16x32_bf16 v[88:91], v[84:87], v[92:95], v[88:91]
	v_mfma_f32_16x16x32_bf16 v[92:95], v[64:67], v[176:179], v[148:151]
	v_mfma_f32_16x16x32_bf16 v[144:147], v[84:87], v[180:183], v[144:147]
	v_mfma_f32_16x16x32_bf16 v[132:135], v[68:71], v[206:209], v[132:135]
	v_mfma_f32_16x16x32_bf16 v[128:131], v[84:87], v[206:209], v[128:131]
	v_mfma_f32_16x16x32_bf16 v[116:119], v[68:71], v[220:223], v[116:119]
	v_mfma_f32_16x16x32_bf16 v[112:115], v[84:87], v[220:223], v[112:115]
	v_mfma_f32_16x16x32_bf16 v[92:95], v[68:71], v[180:183], v[92:95]
	s_barrier
	s_setprio 0
	s_add_i32 s41, s41, s60
	v_lshl_add_u64 v[2:3], s[34:35], 0, v[186:187]
	s_mov_b32 m0, s41
	ds_read_b128 v[148:151], v244 offset:16384
	ds_read_b128 v[160:163], v244 offset:17408
	ds_read_b128 v[176:179], v244 offset:18432
	ds_read_b128 v[180:183], v244 offset:19456
	ds_read_b128 v[202:205], v244 offset:20480
	ds_read_b128 v[206:209], v244 offset:21504
	ds_read_b128 v[210:213], v244 offset:22528
	ds_read_b128 v[220:223], v244 offset:23552
	global_load_lds_dwordx4 v[2:3], off
	s_add_i32 m0, s41, 0x2000
	s_add_u32 s42, s34, 0x40000
	v_lshl_add_u64 v[214:215], s[34:35], 0, v[190:191]
	s_addc_u32 s43, s35, 0
	s_add_i32 s41, s44, s60
	global_load_lds_dwordx4 v[214:215], off
	v_lshl_add_u64 v[6:7], s[42:43], 0, v[186:187]
	s_mov_b32 m0, s41
	v_lshl_add_u64 v[216:217], s[36:37], 0, v[184:185]
	global_load_lds_dwordx4 v[6:7], off
	v_lshl_add_u64 v[6:7], s[42:43], 0, v[190:191]
	s_add_i32 m0, s41, 0x2000
	v_lshl_add_u64 v[228:229], s[36:37], 0, v[188:189]
	global_load_lds_dwordx4 v[6:7], off
	s_mov_b32 m0, s61
	s_nop 0
	global_load_lds_dwordx4 v[216:217], off
	s_mov_b32 m0, s62
	s_nop 0
	global_load_lds_dwordx4 v[228:229], off
	s_waitcnt vmcnt(8)
	s_waitcnt lgkmcnt(0)
	s_barrier
	s_setprio 1
	s_waitcnt lgkmcnt(0)
	v_mfma_f32_16x16x32_bf16 v[108:111], v[40:43], v[148:151], v[108:111]
	v_mfma_f32_16x16x32_bf16 v[104:107], v[48:51], v[148:151], v[104:107]
	v_mfma_f32_16x16x32_bf16 v[76:79], v[40:43], v[176:179], v[76:79]
	v_mfma_f32_16x16x32_bf16 v[72:75], v[48:51], v[176:179], v[72:75]
	v_mfma_f32_16x16x32_bf16 v[36:39], v[40:43], v[202:205], v[36:39]
	v_mfma_f32_16x16x32_bf16 v[32:35], v[48:51], v[202:205], v[32:35]
	v_mfma_f32_16x16x32_bf16 v[20:23], v[40:43], v[210:213], v[20:23]
	v_mfma_f32_16x16x32_bf16 v[16:19], v[48:51], v[210:213], v[16:19]
	v_mfma_f32_16x16x32_bf16 v[108:111], v[44:47], v[160:163], v[108:111]
	v_mfma_f32_16x16x32_bf16 v[104:107], v[52:55], v[160:163], v[104:107]
	v_mfma_f32_16x16x32_bf16 v[76:79], v[44:47], v[180:183], v[76:79]
	v_mfma_f32_16x16x32_bf16 v[72:75], v[52:55], v[180:183], v[72:75]
	v_mfma_f32_16x16x32_bf16 v[36:39], v[44:47], v[206:209], v[36:39]
	v_mfma_f32_16x16x32_bf16 v[32:35], v[52:55], v[206:209], v[32:35]
	v_mfma_f32_16x16x32_bf16 v[20:23], v[44:47], v[220:223], v[20:23]
	v_mfma_f32_16x16x32_bf16 v[16:19], v[52:55], v[220:223], v[16:19]
	s_setprio 0
	s_setprio 1
	v_mfma_f32_16x16x32_bf16 v[28:31], v[64:67], v[202:205], v[28:31]
	v_mfma_f32_16x16x32_bf16 v[24:27], v[80:83], v[202:205], v[24:27]
	v_mfma_f32_16x16x32_bf16 v[12:15], v[64:67], v[210:213], v[12:15]
	v_mfma_f32_16x16x32_bf16 v[6:9], v[80:83], v[210:213], v[8:11]
	v_mfma_f32_16x16x32_bf16 v[40:43], v[64:67], v[148:151], v[100:103]
	v_mfma_f32_16x16x32_bf16 v[44:47], v[80:83], v[148:151], v[96:99]
	v_mfma_f32_16x16x32_bf16 v[48:51], v[64:67], v[176:179], v[60:63]
	v_mfma_f32_16x16x32_bf16 v[52:55], v[80:83], v[176:179], v[56:59]
	v_mfma_f32_16x16x32_bf16 v[28:31], v[68:71], v[206:209], v[28:31]
	v_mfma_f32_16x16x32_bf16 v[24:27], v[84:87], v[206:209], v[24:27]
	v_mfma_f32_16x16x32_bf16 v[12:15], v[68:71], v[220:223], v[12:15]
	v_mfma_f32_16x16x32_bf16 v[6:9], v[84:87], v[220:223], v[6:9]
	v_mfma_f32_16x16x32_bf16 v[40:43], v[68:71], v[160:163], v[40:43]
	v_mfma_f32_16x16x32_bf16 v[44:47], v[84:87], v[160:163], v[44:47]
	v_mfma_f32_16x16x32_bf16 v[48:51], v[68:71], v[180:183], v[48:51]
	v_mfma_f32_16x16x32_bf16 v[52:55], v[84:87], v[180:183], v[52:55]
	s_barrier
	s_setprio 0
	s_add_i32 s41, 0, 0x18000
	v_add_u32_e32 v0, s41, v243
	s_add_i32 s42, 0, 0x1c000
	ds_read_b128 v[56:59], v0
	ds_read_b128 v[60:63], v0 offset:1024
	ds_read_b128 v[64:67], v0 offset:2048
	ds_read_b128 v[68:71], v0 offset:3072
	v_add_u32_e32 v0, s42, v243
	ds_read_b128 v[80:83], v0
	ds_read_b128 v[84:87], v0 offset:1024
	ds_read_b128 v[176:179], v0 offset:2048
	ds_read_b128 v[180:183], v0 offset:3072
	s_add_u32 s36, s36, 0x40000
	s_addc_u32 s37, s37, 0
	s_mov_b32 m0, s63
	v_lshl_add_u64 v[10:11], s[36:37], 0, v[184:185]
	ds_read_b128 v[96:99], v244 offset:32768
	ds_read_b128 v[100:103], v244 offset:33792
	ds_read_b128 v[202:205], v244 offset:34816
	ds_read_b128 v[206:209], v244 offset:35840
	ds_read_b128 v[210:213], v244 offset:36864
	ds_read_b128 v[220:223], v244 offset:37888
	ds_read_b128 v[224:227], v244 offset:38912
	ds_read_b128 v[246:249], v244 offset:39936
	global_load_lds_dwordx4 v[10:11], off
	v_lshl_add_u64 v[10:11], s[36:37], 0, v[188:189]
	s_mov_b32 m0, s64
	s_nop 0
	global_load_lds_dwordx4 v[10:11], off
	s_waitcnt vmcnt(8)
	s_waitcnt lgkmcnt(0)
	s_barrier
	s_setprio 1
	s_waitcnt lgkmcnt(0)
	v_mfma_f32_16x16x32_bf16 v[148:151], v[56:59], v[96:99], v[172:175]
	v_mfma_f32_16x16x32_bf16 v[172:175], v[60:63], v[100:103], v[148:151]
	v_mfma_f32_16x16x32_bf16 v[148:151], v[64:67], v[96:99], v[168:171]
	v_mfma_f32_16x16x32_bf16 v[168:171], v[68:71], v[100:103], v[148:151]
	v_mfma_f32_16x16x32_bf16 v[148:151], v[56:59], v[202:205], v[156:159]
	v_mfma_f32_16x16x32_bf16 v[156:159], v[60:63], v[206:209], v[148:151]
	v_mfma_f32_16x16x32_bf16 v[148:151], v[64:67], v[202:205], v[152:155]
	v_mfma_f32_16x16x32_bf16 v[140:143], v[56:59], v[210:213], v[140:143]
	v_mfma_f32_16x16x32_bf16 v[136:139], v[64:67], v[210:213], v[136:139]
	v_mfma_f32_16x16x32_bf16 v[124:127], v[56:59], v[224:227], v[124:127]
	v_mfma_f32_16x16x32_bf16 v[120:123], v[64:67], v[224:227], v[120:123]
	v_mfma_f32_16x16x32_bf16 v[152:155], v[68:71], v[206:209], v[148:151]
	v_mfma_f32_16x16x32_bf16 v[140:143], v[60:63], v[220:223], v[140:143]
	v_mfma_f32_16x16x32_bf16 v[136:139], v[68:71], v[220:223], v[136:139]
	v_mfma_f32_16x16x32_bf16 v[124:127], v[60:63], v[246:249], v[124:127]
	v_mfma_f32_16x16x32_bf16 v[120:123], v[68:71], v[246:249], v[120:123]
	s_setprio 0
	s_setprio 1
	v_mfma_f32_16x16x32_bf16 v[88:91], v[176:179], v[96:99], v[88:91]
	v_mfma_f32_16x16x32_bf16 v[148:151], v[80:83], v[96:99], v[164:167]
	v_mfma_f32_16x16x32_bf16 v[160:163], v[180:183], v[100:103], v[88:91]
	v_mfma_f32_16x16x32_bf16 v[88:91], v[80:83], v[202:205], v[92:95]
	v_mfma_f32_16x16x32_bf16 v[164:167], v[84:87], v[100:103], v[148:151]
	v_mfma_f32_16x16x32_bf16 v[148:151], v[84:87], v[206:209], v[88:91]
	v_mfma_f32_16x16x32_bf16 v[88:91], v[176:179], v[202:205], v[144:147]
	v_mfma_f32_16x16x32_bf16 v[144:147], v[180:183], v[206:209], v[88:91]
	v_mfma_f32_16x16x32_bf16 v[88:91], v[80:83], v[210:213], v[132:135]
	v_mfma_f32_16x16x32_bf16 v[132:135], v[84:87], v[220:223], v[88:91]
	v_mfma_f32_16x16x32_bf16 v[88:91], v[176:179], v[210:213], v[128:131]
	v_mfma_f32_16x16x32_bf16 v[128:131], v[180:183], v[220:223], v[88:91]
	v_mfma_f32_16x16x32_bf16 v[88:91], v[80:83], v[224:227], v[116:119]
	v_mfma_f32_16x16x32_bf16 v[116:119], v[84:87], v[246:249], v[88:91]
	v_mfma_f32_16x16x32_bf16 v[88:91], v[176:179], v[224:227], v[112:115]
	v_mfma_f32_16x16x32_bf16 v[112:115], v[180:183], v[246:249], v[88:91]
	s_barrier
	s_setprio 0
	s_add_i32 s36, s41, s60
	v_lshl_add_u64 v[2:3], v[2:3], 0, s[50:51]
	s_mov_b32 m0, s36
	s_nop 1
	ds_read_b128 v[88:91], v244 offset:49152
	ds_read_b128 v[92:95], v244 offset:50176
	ds_read_b128 v[202:205], v244 offset:51200
	ds_read_b128 v[206:209], v244 offset:52224
	ds_read_b128 v[210:213], v244 offset:53248
	ds_read_b128 v[220:223], v244 offset:54272
	ds_read_b128 v[224:227], v244 offset:55296
	ds_read_b128 v[246:249], v244 offset:56320
	global_load_lds_dwordx4 v[2:3], off
	s_add_i32 m0, s36, 0x2000
	s_add_u32 s34, s34, 0x40080
	v_lshl_add_u64 v[2:3], v[214:215], 0, s[50:51]
	s_addc_u32 s35, s35, 0
	s_add_i32 s36, s42, s60
	global_load_lds_dwordx4 v[2:3], off
	v_lshl_add_u64 v[2:3], s[34:35], 0, v[186:187]
	s_mov_b32 m0, s36
	s_nop 0
	global_load_lds_dwordx4 v[2:3], off
	v_lshl_add_u64 v[2:3], s[34:35], 0, v[190:191]
	s_add_i32 m0, s36, 0x2000
	s_nop 0
	global_load_lds_dwordx4 v[2:3], off
	v_lshl_add_u64 v[2:3], v[216:217], 0, s[50:51]
	s_mov_b32 m0, s74
	s_nop 0
	global_load_lds_dwordx4 v[2:3], off
	v_lshl_add_u64 v[2:3], v[228:229], 0, s[50:51]
	s_mov_b32 m0, s75
	s_nop 0
	global_load_lds_dwordx4 v[2:3], off
	s_waitcnt vmcnt(8)
	s_waitcnt lgkmcnt(0)
	s_barrier
	s_setprio 1
	s_waitcnt lgkmcnt(0)
	v_mfma_f32_16x16x32_bf16 v[96:99], v[56:59], v[88:91], v[108:111]
	v_mfma_f32_16x16x32_bf16 v[108:111], v[60:63], v[92:95], v[96:99]
	v_mfma_f32_16x16x32_bf16 v[96:99], v[64:67], v[88:91], v[104:107]
	v_mfma_f32_16x16x32_bf16 v[76:79], v[56:59], v[202:205], v[76:79]
	v_mfma_f32_16x16x32_bf16 v[72:75], v[64:67], v[202:205], v[72:75]
	v_mfma_f32_16x16x32_bf16 v[36:39], v[56:59], v[210:213], v[36:39]
	v_mfma_f32_16x16x32_bf16 v[32:35], v[64:67], v[210:213], v[32:35]
	v_mfma_f32_16x16x32_bf16 v[20:23], v[56:59], v[224:227], v[20:23]
	v_mfma_f32_16x16x32_bf16 v[16:19], v[64:67], v[224:227], v[16:19]
	v_mfma_f32_16x16x32_bf16 v[104:107], v[68:71], v[92:95], v[96:99]
	v_mfma_f32_16x16x32_bf16 v[76:79], v[60:63], v[206:209], v[76:79]
	v_mfma_f32_16x16x32_bf16 v[72:75], v[68:71], v[206:209], v[72:75]
	v_mfma_f32_16x16x32_bf16 v[36:39], v[60:63], v[220:223], v[36:39]
	v_mfma_f32_16x16x32_bf16 v[32:35], v[68:71], v[220:223], v[32:35]
	v_mfma_f32_16x16x32_bf16 v[20:23], v[60:63], v[246:249], v[20:23]
	v_mfma_f32_16x16x32_bf16 v[16:19], v[68:71], v[246:249], v[16:19]
	s_setprio 0
	s_setprio 1
	v_mfma_f32_16x16x32_bf16 v[40:43], v[80:83], v[88:91], v[40:43]
	v_mfma_f32_16x16x32_bf16 v[100:103], v[84:87], v[92:95], v[40:43]
	v_mfma_f32_16x16x32_bf16 v[40:43], v[176:179], v[88:91], v[44:47]
	v_mfma_f32_16x16x32_bf16 v[96:99], v[180:183], v[92:95], v[40:43]
	v_mfma_f32_16x16x32_bf16 v[40:43], v[80:83], v[202:205], v[48:51]
	v_mfma_f32_16x16x32_bf16 v[60:63], v[84:87], v[206:209], v[40:43]
	v_mfma_f32_16x16x32_bf16 v[40:43], v[176:179], v[202:205], v[52:55]
	v_mfma_f32_16x16x32_bf16 v[28:31], v[80:83], v[210:213], v[28:31]
	v_mfma_f32_16x16x32_bf16 v[24:27], v[176:179], v[210:213], v[24:27]
	v_mfma_f32_16x16x32_bf16 v[10:13], v[80:83], v[224:227], v[12:15]
	v_mfma_f32_16x16x32_bf16 v[6:9], v[176:179], v[224:227], v[6:9]
	v_mfma_f32_16x16x32_bf16 v[56:59], v[180:183], v[206:209], v[40:43]
	v_mfma_f32_16x16x32_bf16 v[28:31], v[84:87], v[220:223], v[28:31]
	v_mfma_f32_16x16x32_bf16 v[24:27], v[180:183], v[220:223], v[24:27]
	v_mfma_f32_16x16x32_bf16 v[12:15], v[84:87], v[246:249], v[10:13]
	v_mfma_f32_16x16x32_bf16 v[8:11], v[180:183], v[246:249], v[6:9]
	s_barrier
	s_setprio 0
	s_add_i32 s39, s39, 2
	s_add_u32 s8, s8, 0x100
	s_addc_u32 s9, s9, 0
	s_add_u32 s33, s33, 0x100
	s_addc_u32 s38, s38, 0
	s_cmp_gt_u32 s39, 13
	s_cbranch_scc0 .LBB0_347
	s_and_b64 vcc, exec, s[20:21]
	s_cbranch_vccz .LBB0_350
	s_barrier

.LBB0_644:
	s_add_u32 s22, s20, 0xfffc0080
	s_addc_u32 s23, s21, -1
	s_add_i32 s45, 0, 0x10000
	s_cmp_eq_u32 s44, 12
	s_cselect_b32 s25, s11, s23
	s_cselect_b32 s24, s17, s22
	s_cselect_b32 s23, s9, s43
	s_cselect_b32 s22, s41, s42
	s_add_i32 s48, 0, 0x14000
	s_waitcnt vmcnt(0)
	v_add_u32_e32 v146, s45, v160
	v_add_u32_e32 v158, s48, v160
	ds_read_b128 v[134:137], v146
	ds_read_b128 v[138:141], v146 offset:1024
	ds_read_b128 v[142:145], v146 offset:2048
	ds_read_b128 v[146:149], v146 offset:3072
	ds_read_b128 v[164:167], v158
	ds_read_b128 v[168:171], v158 offset:1024
	ds_read_b128 v[172:175], v158 offset:2048
	ds_read_b128 v[176:179], v158 offset:3072
	v_lshl_add_u64 v[158:159], s[20:21], 0, v[154:155]
	s_add_i32 m0, s19, 0xc000
	ds_read_b128 v[180:183], v162
	ds_read_b128 v[184:187], v162 offset:1024
	ds_read_b128 v[188:191], v162 offset:2048
	ds_read_b128 v[192:195], v162 offset:3072
	ds_read_b128 v[196:199], v162 offset:4096
	ds_read_b128 v[200:203], v162 offset:5120
	ds_read_b128 v[204:207], v162 offset:6144
	ds_read_b128 v[208:211], v162 offset:7168
	global_load_lds_dwordx4 v[158:159], off
	v_lshl_add_u64 v[158:159], s[20:21], 0, v[156:157]
	s_add_i32 m0, s19, 0xe000
	s_nop 0
	global_load_lds_dwordx4 v[158:159], off
	s_waitcnt vmcnt(8)
	s_waitcnt lgkmcnt(0)
	s_barrier
	s_setprio 1
	s_waitcnt lgkmcnt(0)
	v_mfma_f32_16x16x32_bf16 v[130:133], v[134:137], v[180:183], v[130:133]
	v_mfma_f32_16x16x32_bf16 v[126:129], v[142:145], v[180:183], v[126:129]
	v_mfma_f32_16x16x32_bf16 v[118:121], v[134:137], v[188:191], v[118:121]
	v_mfma_f32_16x16x32_bf16 v[110:113], v[142:145], v[188:191], v[110:113]
	v_mfma_f32_16x16x32_bf16 v[102:105], v[134:137], v[196:199], v[102:105]
	v_mfma_f32_16x16x32_bf16 v[94:97], v[142:145], v[196:199], v[94:97]
	v_mfma_f32_16x16x32_bf16 v[86:89], v[134:137], v[204:207], v[86:89]
	v_mfma_f32_16x16x32_bf16 v[78:81], v[142:145], v[204:207], v[78:81]
	v_mfma_f32_16x16x32_bf16 v[130:133], v[138:141], v[184:187], v[130:133]
	v_mfma_f32_16x16x32_bf16 v[126:129], v[146:149], v[184:187], v[126:129]
	v_mfma_f32_16x16x32_bf16 v[118:121], v[138:141], v[192:195], v[118:121]
	v_mfma_f32_16x16x32_bf16 v[110:113], v[146:149], v[192:195], v[110:113]
	v_mfma_f32_16x16x32_bf16 v[102:105], v[138:141], v[200:203], v[102:105]
	v_mfma_f32_16x16x32_bf16 v[94:97], v[146:149], v[200:203], v[94:97]
	v_mfma_f32_16x16x32_bf16 v[86:89], v[138:141], v[208:211], v[86:89]
	v_mfma_f32_16x16x32_bf16 v[78:81], v[146:149], v[208:211], v[78:81]
	s_setprio 0
	s_setprio 1
	v_mfma_f32_16x16x32_bf16 v[122:125], v[164:167], v[180:183], v[122:125]
	v_mfma_f32_16x16x32_bf16 v[114:117], v[172:175], v[180:183], v[114:117]
	v_mfma_f32_16x16x32_bf16 v[106:109], v[164:167], v[188:191], v[106:109]
	v_mfma_f32_16x16x32_bf16 v[98:101], v[172:175], v[188:191], v[98:101]
	v_mfma_f32_16x16x32_bf16 v[90:93], v[164:167], v[196:199], v[90:93]
	v_mfma_f32_16x16x32_bf16 v[82:85], v[172:175], v[196:199], v[82:85]
	v_mfma_f32_16x16x32_bf16 v[74:77], v[164:167], v[204:207], v[74:77]
	v_mfma_f32_16x16x32_bf16 v[70:73], v[172:175], v[204:207], v[70:73]
	v_mfma_f32_16x16x32_bf16 v[122:125], v[168:171], v[184:187], v[122:125]
	v_mfma_f32_16x16x32_bf16 v[114:117], v[176:179], v[184:187], v[114:117]
	v_mfma_f32_16x16x32_bf16 v[106:109], v[168:171], v[192:195], v[106:109]
	v_mfma_f32_16x16x32_bf16 v[98:101], v[176:179], v[192:195], v[98:101]
	v_mfma_f32_16x16x32_bf16 v[90:93], v[168:171], v[200:203], v[90:93]
	v_mfma_f32_16x16x32_bf16 v[82:85], v[176:179], v[200:203], v[82:85]
	v_mfma_f32_16x16x32_bf16 v[74:77], v[168:171], v[208:211], v[74:77]
	v_mfma_f32_16x16x32_bf16 v[70:73], v[176:179], v[208:211], v[70:73]
	s_barrier
	s_setprio 0
	s_add_i32 s45, s45, s30
	v_lshl_add_u64 v[158:159], s[22:23], 0, v[0:1]
	s_mov_b32 m0, s45
	ds_read_b128 v[180:183], v162 offset:16384
	ds_read_b128 v[184:187], v162 offset:17408
	ds_read_b128 v[188:191], v162 offset:18432
	ds_read_b128 v[192:195], v162 offset:19456
	ds_read_b128 v[196:199], v162 offset:20480
	ds_read_b128 v[200:203], v162 offset:21504
	ds_read_b128 v[204:207], v162 offset:22528
	ds_read_b128 v[208:211], v162 offset:23552
	global_load_lds_dwordx4 v[158:159], off
	s_add_i32 m0, s45, 0x2000
	s_add_u32 s60, s22, 0x40000
	v_lshl_add_u64 v[212:213], s[22:23], 0, v[152:153]
	s_addc_u32 s61, s23, 0
	s_add_i32 s45, s48, s30
	global_load_lds_dwordx4 v[212:213], off
	v_lshl_add_u64 v[214:215], s[60:61], 0, v[0:1]
	s_mov_b32 m0, s45
	v_lshl_add_u64 v[216:217], s[24:25], 0, v[150:151]
	global_load_lds_dwordx4 v[214:215], off
	v_lshl_add_u64 v[214:215], s[60:61], 0, v[152:153]
	s_add_i32 m0, s45, 0x2000
	s_nop 0
	global_load_lds_dwordx4 v[214:215], off
	v_lshl_add_u64 v[214:215], s[24:25], 0, v[2:3]
	s_mov_b32 m0, s19
	s_nop 0
	global_load_lds_dwordx4 v[214:215], off
	s_mov_b32 m0, s31
	s_nop 0
	global_load_lds_dwordx4 v[216:217], off
	s_waitcnt vmcnt(8)
	s_waitcnt lgkmcnt(0)
	s_barrier
	s_setprio 1
	s_waitcnt lgkmcnt(0)
	v_mfma_f32_16x16x32_bf16 v[66:69], v[134:137], v[180:183], v[66:69]
	v_mfma_f32_16x16x32_bf16 v[62:65], v[142:145], v[180:183], v[62:65]
	v_mfma_f32_16x16x32_bf16 v[54:57], v[134:137], v[188:191], v[54:57]
	v_mfma_f32_16x16x32_bf16 v[46:49], v[142:145], v[188:191], v[46:49]
	v_mfma_f32_16x16x32_bf16 v[38:41], v[134:137], v[196:199], v[38:41]
	v_mfma_f32_16x16x32_bf16 v[30:33], v[142:145], v[196:199], v[30:33]
	v_mfma_f32_16x16x32_bf16 v[22:25], v[134:137], v[204:207], v[22:25]
	v_mfma_f32_16x16x32_bf16 v[14:17], v[142:145], v[204:207], v[14:17]
	v_mfma_f32_16x16x32_bf16 v[66:69], v[138:141], v[184:187], v[66:69]
	v_mfma_f32_16x16x32_bf16 v[62:65], v[146:149], v[184:187], v[62:65]
	v_mfma_f32_16x16x32_bf16 v[54:57], v[138:141], v[192:195], v[54:57]
	v_mfma_f32_16x16x32_bf16 v[46:49], v[146:149], v[192:195], v[46:49]
	v_mfma_f32_16x16x32_bf16 v[38:41], v[138:141], v[200:203], v[38:41]
	v_mfma_f32_16x16x32_bf16 v[30:33], v[146:149], v[200:203], v[30:33]
	v_mfma_f32_16x16x32_bf16 v[22:25], v[138:141], v[208:211], v[22:25]
	v_mfma_f32_16x16x32_bf16 v[14:17], v[146:149], v[208:211], v[14:17]
	s_setprio 0
	s_setprio 1
	v_mfma_f32_16x16x32_bf16 v[58:61], v[164:167], v[180:183], v[58:61]
	v_mfma_f32_16x16x32_bf16 v[50:53], v[172:175], v[180:183], v[50:53]
	v_mfma_f32_16x16x32_bf16 v[42:45], v[164:167], v[188:191], v[42:45]
	v_mfma_f32_16x16x32_bf16 v[34:37], v[172:175], v[188:191], v[34:37]
	v_mfma_f32_16x16x32_bf16 v[26:29], v[164:167], v[196:199], v[26:29]
	v_mfma_f32_16x16x32_bf16 v[18:21], v[172:175], v[196:199], v[18:21]
	v_mfma_f32_16x16x32_bf16 v[10:13], v[164:167], v[204:207], v[10:13]
	v_mfma_f32_16x16x32_bf16 v[6:9], v[172:175], v[204:207], v[6:9]
	v_mfma_f32_16x16x32_bf16 v[58:61], v[168:171], v[184:187], v[58:61]
	v_mfma_f32_16x16x32_bf16 v[50:53], v[176:179], v[184:187], v[50:53]
	v_mfma_f32_16x16x32_bf16 v[42:45], v[168:171], v[192:195], v[42:45]
	v_mfma_f32_16x16x32_bf16 v[34:37], v[176:179], v[192:195], v[34:37]
	v_mfma_f32_16x16x32_bf16 v[26:29], v[168:171], v[200:203], v[26:29]
	v_mfma_f32_16x16x32_bf16 v[18:21], v[176:179], v[200:203], v[18:21]
	v_mfma_f32_16x16x32_bf16 v[10:13], v[168:171], v[208:211], v[10:13]
	v_mfma_f32_16x16x32_bf16 v[6:9], v[176:179], v[208:211], v[6:9]
	s_barrier
	s_setprio 0
	s_add_i32 s45, 0, 0x18000
	s_add_i32 s48, 0, 0x1c000
	v_add_u32_e32 v146, s45, v160
	v_add_u32_e32 v163, s48, v160
	ds_read_b128 v[134:137], v146
	ds_read_b128 v[138:141], v146 offset:1024
	ds_read_b128 v[142:145], v146 offset:2048
	ds_read_b128 v[146:149], v146 offset:3072
	ds_read_b128 v[164:167], v163
	ds_read_b128 v[168:171], v163 offset:1024
	ds_read_b128 v[172:175], v163 offset:2048
	ds_read_b128 v[176:179], v163 offset:3072
	s_add_u32 s24, s24, 0x40000
	s_addc_u32 s25, s25, 0
	s_mov_b32 m0, s33
	v_lshl_add_u64 v[220:221], s[24:25], 0, v[2:3]
	ds_read_b128 v[180:183], v162 offset:32768
	ds_read_b128 v[184:187], v162 offset:33792
	ds_read_b128 v[188:191], v162 offset:34816
	ds_read_b128 v[192:195], v162 offset:35840
	ds_read_b128 v[196:199], v162 offset:36864
	ds_read_b128 v[200:203], v162 offset:37888
	ds_read_b128 v[204:207], v162 offset:38912
	ds_read_b128 v[208:211], v162 offset:39936
	global_load_lds_dwordx4 v[220:221], off
	v_lshl_add_u64 v[220:221], s[24:25], 0, v[150:151]
	s_mov_b32 m0, s34
	s_nop 0
	global_load_lds_dwordx4 v[220:221], off
	s_waitcnt vmcnt(8)
	s_waitcnt lgkmcnt(0)
	s_barrier
	s_setprio 1
	s_waitcnt lgkmcnt(0)
	v_mfma_f32_16x16x32_bf16 v[130:133], v[134:137], v[180:183], v[130:133]
	v_mfma_f32_16x16x32_bf16 v[126:129], v[142:145], v[180:183], v[126:129]
	v_mfma_f32_16x16x32_bf16 v[118:121], v[134:137], v[188:191], v[118:121]
	v_mfma_f32_16x16x32_bf16 v[110:113], v[142:145], v[188:191], v[110:113]
	v_mfma_f32_16x16x32_bf16 v[102:105], v[134:137], v[196:199], v[102:105]
	v_mfma_f32_16x16x32_bf16 v[94:97], v[142:145], v[196:199], v[94:97]
	v_mfma_f32_16x16x32_bf16 v[86:89], v[134:137], v[204:207], v[86:89]
	v_mfma_f32_16x16x32_bf16 v[78:81], v[142:145], v[204:207], v[78:81]
	v_mfma_f32_16x16x32_bf16 v[130:133], v[138:141], v[184:187], v[130:133]
	v_mfma_f32_16x16x32_bf16 v[126:129], v[146:149], v[184:187], v[126:129]
	v_mfma_f32_16x16x32_bf16 v[118:121], v[138:141], v[192:195], v[118:121]
	v_mfma_f32_16x16x32_bf16 v[110:113], v[146:149], v[192:195], v[110:113]
	v_mfma_f32_16x16x32_bf16 v[102:105], v[138:141], v[200:203], v[102:105]
	v_mfma_f32_16x16x32_bf16 v[94:97], v[146:149], v[200:203], v[94:97]
	v_mfma_f32_16x16x32_bf16 v[86:89], v[138:141], v[208:211], v[86:89]
	v_mfma_f32_16x16x32_bf16 v[78:81], v[146:149], v[208:211], v[78:81]
	s_setprio 0
	s_setprio 1
	v_mfma_f32_16x16x32_bf16 v[122:125], v[164:167], v[180:183], v[122:125]
	v_mfma_f32_16x16x32_bf16 v[114:117], v[172:175], v[180:183], v[114:117]
	v_mfma_f32_16x16x32_bf16 v[106:109], v[164:167], v[188:191], v[106:109]
	v_mfma_f32_16x16x32_bf16 v[98:101], v[172:175], v[188:191], v[98:101]
	v_mfma_f32_16x16x32_bf16 v[90:93], v[164:167], v[196:199], v[90:93]
	v_mfma_f32_16x16x32_bf16 v[82:85], v[172:175], v[196:199], v[82:85]
	v_mfma_f32_16x16x32_bf16 v[74:77], v[164:167], v[204:207], v[74:77]
	v_mfma_f32_16x16x32_bf16 v[70:73], v[172:175], v[204:207], v[70:73]
	v_mfma_f32_16x16x32_bf16 v[122:125], v[168:171], v[184:187], v[122:125]
	v_mfma_f32_16x16x32_bf16 v[114:117], v[176:179], v[184:187], v[114:117]
	v_mfma_f32_16x16x32_bf16 v[106:109], v[168:171], v[192:195], v[106:109]
	v_mfma_f32_16x16x32_bf16 v[98:101], v[176:179], v[192:195], v[98:101]
	v_mfma_f32_16x16x32_bf16 v[90:93], v[168:171], v[200:203], v[90:93]
	v_mfma_f32_16x16x32_bf16 v[82:85], v[176:179], v[200:203], v[82:85]
	v_mfma_f32_16x16x32_bf16 v[74:77], v[168:171], v[208:211], v[74:77]
	v_mfma_f32_16x16x32_bf16 v[70:73], v[176:179], v[208:211], v[70:73]
	s_barrier
	s_setprio 0
	s_add_i32 s24, s45, s30
	v_lshl_add_u64 v[158:159], v[158:159], 0, s[50:51]
	s_mov_b32 m0, s24
	ds_read_b128 v[180:183], v162 offset:49152
	ds_read_b128 v[184:187], v162 offset:50176
	ds_read_b128 v[188:191], v162 offset:51200
	ds_read_b128 v[192:195], v162 offset:52224
	ds_read_b128 v[196:199], v162 offset:53248
	ds_read_b128 v[200:203], v162 offset:54272
	ds_read_b128 v[204:207], v162 offset:55296
	ds_read_b128 v[208:211], v162 offset:56320
	global_load_lds_dwordx4 v[158:159], off
	s_add_i32 m0, s24, 0x2000
	s_add_u32 s22, s22, 0x40080
	v_lshl_add_u64 v[158:159], v[212:213], 0, s[50:51]
	s_addc_u32 s23, s23, 0
	s_add_i32 s24, s48, s30
	global_load_lds_dwordx4 v[158:159], off
	v_lshl_add_u64 v[158:159], s[22:23], 0, v[0:1]
	s_mov_b32 m0, s24
	s_nop 0
	global_load_lds_dwordx4 v[158:159], off
	v_lshl_add_u64 v[158:159], s[22:23], 0, v[152:153]
	s_add_i32 m0, s24, 0x2000
	s_nop 0
	global_load_lds_dwordx4 v[158:159], off
	v_lshl_add_u64 v[158:159], v[214:215], 0, s[50:51]
	s_mov_b32 m0, s35
	s_nop 0
	global_load_lds_dwordx4 v[158:159], off
	v_lshl_add_u64 v[158:159], v[216:217], 0, s[50:51]
	s_mov_b32 m0, s36
	s_nop 0
	global_load_lds_dwordx4 v[158:159], off
	s_waitcnt vmcnt(8)
	s_waitcnt lgkmcnt(0)
	s_barrier
	s_setprio 1
	s_waitcnt lgkmcnt(0)
	v_mfma_f32_16x16x32_bf16 v[66:69], v[134:137], v[180:183], v[66:69]
	v_mfma_f32_16x16x32_bf16 v[62:65], v[142:145], v[180:183], v[62:65]
	v_mfma_f32_16x16x32_bf16 v[54:57], v[134:137], v[188:191], v[54:57]
	v_mfma_f32_16x16x32_bf16 v[46:49], v[142:145], v[188:191], v[46:49]
	v_mfma_f32_16x16x32_bf16 v[38:41], v[134:137], v[196:199], v[38:41]
	v_mfma_f32_16x16x32_bf16 v[30:33], v[142:145], v[196:199], v[30:33]
	v_mfma_f32_16x16x32_bf16 v[22:25], v[134:137], v[204:207], v[22:25]
	v_mfma_f32_16x16x32_bf16 v[14:17], v[142:145], v[204:207], v[14:17]
	v_mfma_f32_16x16x32_bf16 v[66:69], v[138:141], v[184:187], v[66:69]
	v_mfma_f32_16x16x32_bf16 v[62:65], v[146:149], v[184:187], v[62:65]
	v_mfma_f32_16x16x32_bf16 v[54:57], v[138:141], v[192:195], v[54:57]
	v_mfma_f32_16x16x32_bf16 v[46:49], v[146:149], v[192:195], v[46:49]
	v_mfma_f32_16x16x32_bf16 v[38:41], v[138:141], v[200:203], v[38:41]
	v_mfma_f32_16x16x32_bf16 v[30:33], v[146:149], v[200:203], v[30:33]
	v_mfma_f32_16x16x32_bf16 v[22:25], v[138:141], v[208:211], v[22:25]
	v_mfma_f32_16x16x32_bf16 v[14:17], v[146:149], v[208:211], v[14:17]
	s_setprio 0
	s_setprio 1
	v_mfma_f32_16x16x32_bf16 v[58:61], v[164:167], v[180:183], v[58:61]
	v_mfma_f32_16x16x32_bf16 v[50:53], v[172:175], v[180:183], v[50:53]
	v_mfma_f32_16x16x32_bf16 v[42:45], v[164:167], v[188:191], v[42:45]
	v_mfma_f32_16x16x32_bf16 v[34:37], v[172:175], v[188:191], v[34:37]
	v_mfma_f32_16x16x32_bf16 v[26:29], v[164:167], v[196:199], v[26:29]
	v_mfma_f32_16x16x32_bf16 v[18:21], v[172:175], v[196:199], v[18:21]
	v_mfma_f32_16x16x32_bf16 v[10:13], v[164:167], v[204:207], v[10:13]
	v_mfma_f32_16x16x32_bf16 v[6:9], v[172:175], v[204:207], v[6:9]
	v_mfma_f32_16x16x32_bf16 v[58:61], v[168:171], v[184:187], v[58:61]
	v_mfma_f32_16x16x32_bf16 v[50:53], v[176:179], v[184:187], v[50:53]
	v_mfma_f32_16x16x32_bf16 v[42:45], v[168:171], v[192:195], v[42:45]
	v_mfma_f32_16x16x32_bf16 v[34:37], v[176:179], v[192:195], v[34:37]
	v_mfma_f32_16x16x32_bf16 v[26:29], v[168:171], v[200:203], v[26:29]
	v_mfma_f32_16x16x32_bf16 v[18:21], v[176:179], v[200:203], v[18:21]
	v_mfma_f32_16x16x32_bf16 v[10:13], v[168:171], v[208:211], v[10:13]
	v_mfma_f32_16x16x32_bf16 v[6:9], v[176:179], v[208:211], v[6:9]
	s_barrier
	s_setprio 0
	s_add_i32 s44, s44, 2
	s_add_u32 s20, s20, 0x100
	s_addc_u32 s21, s21, 0
	s_add_u32 s42, s42, 0x100
	s_addc_u32 s43, s43, 0
	s_cmp_gt_u32 s44, 13
	s_cbranch_scc0 .LBB0_644
	s_and_b64 vcc, exec, s[6:7]
	s_cbranch_vccz .LBB0_647
	s_barrier
